# GLA in-chunk cumsum quad offsets via permlane16/32 swaps (all 11 runs) on top of the other permlane-swap reductions
# baseline (speedup 1.0000x reference)
.LBB0_469:
	v_mov_b32_e32 v252, v183
	v_mov_b32_e32 v253, v183
	s_nop 1
	v_permlane16_swap_b32_e32 v252, v253
	v_mov_b32_e32 v254, v252
	v_mov_b32_e32 v255, v253
	s_nop 1
	v_permlane32_swap_b32_e32 v252, v254
	v_permlane32_swap_b32_e32 v253, v255
	v_mov_b32_e32 v96, v252
	v_mov_b32_e32 v97, v253
	v_mov_b32_e32 v95, v254
	v_mov_b32_e32 v98, v255
	s_mov_b64 s[52:53], -1
	s_and_b64 vcc, exec, s[48:49]
	s_cbranch_vccz .LBB0_471
	s_waitcnt lgkmcnt(0)
	v_cndmask_b32_e64 v94, v98, 0, s[6:7]
	v_cndmask_b32_e64 v98, 0, v95, s[8:9]
	v_add_f32_e32 v94, v98, v94
	v_cndmask_b32_e64 v98, 0, v97, s[10:11]
	v_add_f32_e32 v94, v98, v94
	s_mov_b64 s[52:53], 0

.LBB0_484:
	v_mov_b32_e32 v252, v174
	v_mov_b32_e32 v253, v174
	s_nop 1
	v_permlane16_swap_b32_e32 v252, v253
	v_mov_b32_e32 v254, v252
	v_mov_b32_e32 v255, v253
	s_nop 1
	v_permlane32_swap_b32_e32 v252, v254
	v_permlane32_swap_b32_e32 v253, v255
	v_mov_b32_e32 v92, v252
	v_mov_b32_e32 v93, v253
	v_mov_b32_e32 v91, v254
	v_mov_b32_e32 v94, v255
	s_and_b64 vcc, exec, s[30:31]
	s_mov_b64 s[30:31], -1
	s_cbranch_vccnz .LBB0_486
	s_waitcnt lgkmcnt(0)
	v_cndmask_b32_e64 v90, v94, 0, s[6:7]
	v_cndmask_b32_e64 v94, 0, v91, s[8:9]
	v_add_f32_e32 v90, v94, v90
	v_cndmask_b32_e64 v94, 0, v93, s[10:11]
	v_add_f32_e32 v90, v94, v90
	s_mov_b64 s[30:31], 0

.LBB0_502:
	s_add_u32 s50, s53, s46
	s_addc_u32 s51, s77, s47
	s_add_u32 s31, s43, s46
	s_addc_u32 s48, s52, s47
	s_add_u32 s80, s31, s76
	s_addc_u32 s81, s48, 0
	s_and_b32 s79, s78, 1
	s_cmp_eq_u32 s79, 0
	s_cselect_b64 s[48:49], -1, 0
	s_and_b64 s[82:83], s[48:49], exec
	s_cselect_b32 s31, 0xf0, s67
	v_add3_u32 v1, s31, v126, v133
	ds_read2_b32 v[74:75], v1 offset1:4
	v_lshl_add_u64 v[76:77], s[50:51], 0, v[112:113]
	ds_read2_b32 v[82:83], v1 offset0:64 offset1:68
	global_load_dwordx4 v[94:97], v[76:77], off
	global_load_dwordx4 v[98:101], v[76:77], off offset:1024
	ds_read2_b32 v[108:109], v1 offset0:8 offset1:12
	v_lshl_add_u64 v[84:85], s[80:81], 0, v[114:115]
	s_mov_b32 s31, 0x3d800000
	s_waitcnt vmcnt(6) lgkmcnt(2)
	v_mfma_f32_16x16x4_f32 v[70:73], v74, v102, 0
	v_add_co_u32_e32 v74, vcc, s63, v76
	s_waitcnt vmcnt(5)
	v_mfma_f32_16x16x4_f32 v[70:73], v75, v103, v[70:73]
	v_addc_co_u32_e32 v75, vcc, 0, v77, vcc
	global_load_dwordx4 v[86:89], v[74:75], off
	global_load_dwordx4 v[90:93], v[74:75], off offset:1024
	v_add_co_u32_e32 v74, vcc, s64, v84
	s_nop 1
	v_addc_co_u32_e32 v75, vcc, 0, v85, vcc
	s_waitcnt vmcnt(6) lgkmcnt(0)
	v_mfma_f32_16x16x4_f32 v[160:163], v108, v104, v[70:73]
	v_add_co_u32_e32 v168, vcc, s63, v84
	global_load_dwordx4 v[70:73], v[84:85], off
	s_nop 0
	global_load_dwordx4 v[74:77], v[74:75], off
	v_addc_co_u32_e32 v169, vcc, 0, v85, vcc
	v_mfma_f32_16x16x4_f32 v[78:81], v82, v102, 0
	v_add_co_u32_e32 v82, vcc, s65, v84
	s_waitcnt vmcnt(7)
	v_mfma_f32_16x16x4_f32 v[160:163], v109, v105, v[160:163]
	v_mfma_f32_16x16x4_f32 v[164:167], v83, v103, v[78:81]
	v_addc_co_u32_e32 v83, vcc, 0, v85, vcc
	s_nop 4
	global_load_dwordx4 v[78:81], v[168:169], off
	s_nop 0
	global_load_dwordx4 v[82:85], v[82:83], off
	ds_read2_b32 v[168:169], v1 offset0:72 offset1:76
	s_waitcnt vmcnt(8)
	v_add_f32_e32 v107, v106, v160
	v_min_f32_e32 v170, 0, v107
	v_mul_f32_e64 v107, |v107|, s68
	v_exp_f32_e32 v107, v107
	v_add_f32_e32 v108, v106, v161
	v_add_f32_e32 v109, v106, v162
	v_mul_f32_e64 v160, |v108|, s68
	v_mul_f32_e64 v161, |v109|, s68
	v_exp_f32_e32 v160, v160
	v_exp_f32_e32 v161, v161
	v_add_f32_e32 v107, 1.0, v107
	v_log_f32_e32 v107, v107
	s_waitcnt lgkmcnt(0)
	v_mfma_f32_16x16x4_f32 v[164:167], v168, v104, v[164:167]
	v_add_f32_e32 v160, 1.0, v160
	v_add_f32_e32 v161, 1.0, v161
	v_log_f32_e32 v160, v160
	v_fmac_f32_e32 v170, 0xbf317218, v107
	v_log_f32_e32 v107, v161
	v_min_f32_e32 v171, 0, v108
	v_min_f32_e32 v172, 0, v109
	v_fmac_f32_e32 v171, 0xbf317218, v160
	v_fmac_f32_e32 v172, 0xbf317218, v107
	v_add_f32_e32 v107, v106, v163
	v_mfma_f32_16x16x4_f32 v[160:163], v169, v105, v[164:167]
	v_mul_f32_e64 v108, |v107|, s68
	v_exp_f32_e32 v168, v108
	v_min_f32_e32 v107, 0, v107
	v_add_f32_e32 v165, 1.0, v168
	v_log_f32_e32 v165, v165
	s_nop 4
	v_add_f32_e32 v160, v106, v160
	v_mul_f32_e64 v108, |v160|, s68
	v_exp_f32_e32 v164, v108
	ds_read2_b32 v[108:109], v1 offset0:128 offset1:132
	v_min_f32_e32 v173, 0, v160
	v_fmac_f32_e32 v107, 0xbf317218, v165
	v_add_f32_e32 v164, 1.0, v164
	v_log_f32_e32 v164, v164
	ds_read2_b32 v[168:169], v1 offset0:136 offset1:140
	v_add_f32_e32 v174, v106, v162
	v_add_f32_e32 v176, v106, v163
	v_fmac_f32_e32 v173, 0xbf317218, v164
	s_waitcnt lgkmcnt(1)
	v_mfma_f32_16x16x4_f32 v[164:167], v108, v102, 0
	v_add_f32_e32 v108, v106, v161
	v_mul_f32_e64 v160, |v108|, s68
	v_mul_f32_e64 v161, |v174|, s68
	v_exp_f32_e32 v160, v160
	v_exp_f32_e32 v161, v161
	v_min_f32_e32 v175, 0, v108
	v_mul_f32_e64 v177, |v176|, s68
	v_mfma_f32_16x16x4_f32 v[164:167], v109, v103, v[164:167]
	v_add_f32_e32 v108, 1.0, v160
	v_add_f32_e32 v109, 1.0, v161
	v_log_f32_e32 v108, v108
	v_log_f32_e32 v109, v109
	v_min_f32_e32 v174, 0, v174
	v_min_f32_e32 v176, 0, v176
	v_fmac_f32_e32 v175, 0xbf317218, v108
	s_waitcnt lgkmcnt(0)
	v_mfma_f32_16x16x4_f32 v[160:163], v168, v104, v[164:167]
	s_nop 0
	v_exp_f32_e32 v164, v177
	v_fmac_f32_e32 v174, 0xbf317218, v109
	v_add_f32_e32 v108, 1.0, v164
	v_log_f32_e32 v164, v108
	ds_read2_b32 v[108:109], v1 offset0:192 offset1:196
	v_mfma_f32_16x16x4_f32 v[160:163], v169, v105, v[160:163]
	v_fmac_f32_e32 v176, 0xbf317218, v164
	s_nop 8
	v_add_f32_e32 v160, v106, v160
	v_mul_f32_e64 v164, |v160|, s68
	v_exp_f32_e32 v168, v164
	s_waitcnt lgkmcnt(0)
	v_mfma_f32_16x16x4_f32 v[164:167], v108, v102, 0
	v_add_f32_e32 v161, v106, v161
	v_mul_f32_e64 v169, |v161|, s68
	v_exp_f32_e32 v108, v169
	v_min_f32_e32 v177, 0, v160
	v_add_f32_e32 v160, 1.0, v168
	ds_read2_b32 v[168:169], v1 offset0:200 offset1:204
	v_add_f32_e32 v108, 1.0, v108
	v_mfma_f32_16x16x4_f32 v[164:167], v109, v103, v[164:167]
	v_log_f32_e32 v160, v160
	v_log_f32_e32 v108, v108
	v_min_f32_e32 v1, 0, v161
	v_add_f32_e32 v178, v106, v163
	v_fmac_f32_e32 v177, 0xbf317218, v160
	v_fmac_f32_e32 v1, 0xbf317218, v108
	v_add_f32_e32 v108, v106, v162
	s_waitcnt lgkmcnt(0)
	v_mfma_f32_16x16x4_f32 v[160:163], v168, v104, v[164:167]
	v_mul_f32_e64 v109, |v108|, s68
	v_exp_f32_e32 v109, v109
	v_mul_f32_e64 v164, |v178|, s68
	v_exp_f32_e32 v164, v164
	v_min_f32_e32 v108, 0, v108
	v_add_f32_e32 v109, 1.0, v109
	v_log_f32_e32 v109, v109
	v_mfma_f32_16x16x4_f32 v[160:163], v169, v105, v[160:163]
	v_add_f32_e32 v164, 1.0, v164
	v_log_f32_e32 v164, v164
	v_fmac_f32_e32 v108, 0xbf317218, v109
	v_min_f32_e32 v109, 0, v178
	v_fmac_f32_e32 v109, 0xbf317218, v164
	s_nop 4
	v_add_f32_e32 v160, v106, v160
	v_mul_f32_e64 v165, |v160|, s68
	v_exp_f32_e32 v165, v165
	v_add_f32_e32 v161, v106, v161
	v_min_f32_e32 v160, 0, v160
	v_add_f32_e32 v162, v106, v162
	v_add_f32_e32 v164, 1.0, v165
	v_mul_f32_e64 v165, |v161|, s68
	v_log_f32_e32 v164, v164
	v_exp_f32_e32 v165, v165
	v_add_f32_e32 v163, v106, v163
	v_mul_f32_e64 v166, |v163|, s68
	v_fmac_f32_e32 v160, 0xbf317218, v164
	v_add_f32_e32 v164, 1.0, v165
	v_mul_f32_e64 v165, |v162|, s68
	v_log_f32_e32 v164, v164
	v_exp_f32_e32 v165, v165
	v_exp_f32_e32 v166, v166
	v_min_f32_e32 v161, 0, v161
	v_fmac_f32_e32 v161, 0xbf317218, v164
	v_add_f32_e32 v164, 1.0, v165
	v_log_f32_e32 v164, v164
	v_add_f32_e32 v165, 1.0, v166
	v_log_f32_e32 v165, v165
	v_min_f32_e32 v162, 0, v162
	v_fmac_f32_e32 v162, 0xbf317218, v164
	v_min_f32_e32 v163, 0, v163
	v_fma_f32 v164, v170, s31, 0
	v_fmac_f32_e32 v163, 0xbf317218, v165
	v_fmamk_f32 v165, v171, 0x3d800000, v164
	v_fmamk_f32 v166, v172, 0x3d800000, v165
	v_fmamk_f32 v107, v107, 0x3d800000, v166
	v_fmamk_f32 v167, v173, 0x3d800000, v107
	v_fmamk_f32 v168, v175, 0x3d800000, v167
	v_fmamk_f32 v169, v174, 0x3d800000, v168
	v_fmamk_f32 v170, v176, 0x3d800000, v169
	v_fmamk_f32 v171, v177, 0x3d800000, v170
	v_fmamk_f32 v1, v1, 0x3d800000, v171
	v_fmamk_f32 v108, v108, 0x3d800000, v1
	v_fmamk_f32 v109, v109, 0x3d800000, v108
	v_fmamk_f32 v160, v160, 0x3d800000, v109
	v_fmamk_f32 v161, v161, 0x3d800000, v160
	v_fmamk_f32 v162, v162, 0x3d800000, v161
	v_fmamk_f32 v163, v163, 0x3d800000, v162
	v_mov_b32_e32 v252, v163
	v_mov_b32_e32 v253, v163
	s_nop 1
	v_permlane16_swap_b32_e32 v252, v253
	v_mov_b32_e32 v254, v252
	v_mov_b32_e32 v255, v253
	s_nop 1
	v_permlane32_swap_b32_e32 v252, v254
	v_permlane32_swap_b32_e32 v253, v255
	v_mov_b32_e32 v172, v252
	v_mov_b32_e32 v173, v253
	v_mov_b32_e32 v174, v254
	s_waitcnt lgkmcnt(2)
	v_cndmask_b32_e64 v172, v172, 0, s[10:11]
	s_waitcnt lgkmcnt(1)
	v_cndmask_b32_e64 v173, 0, v173, s[12:13]
	v_add_f32_e32 v172, v172, v173
	s_waitcnt lgkmcnt(0)
	v_cndmask_b32_e64 v173, 0, v174, s[6:7]
	v_add_f32_e32 v172, v172, v173
	v_add_f32_e32 v164, v164, v172
	v_add_f32_e32 v165, v165, v172
	ds_write2st64_b32 v141, v164, v165 offset0:24 offset1:26
	v_add_f32_e32 v164, v166, v172
	v_add_f32_e32 v107, v107, v172
	ds_write2st64_b32 v141, v164, v107 offset0:28 offset1:30
	v_add_f32_e32 v107, v167, v172
	v_add_f32_e32 v164, v168, v172
	ds_write2st64_b32 v141, v107, v164 offset0:32 offset1:34
	v_add_f32_e32 v107, v169, v172
	v_add_f32_e32 v164, v170, v172
	ds_write2st64_b32 v141, v107, v164 offset0:36 offset1:38
	v_add_f32_e32 v107, v171, v172
	v_add_f32_e32 v1, v1, v172
	ds_write2st64_b32 v141, v107, v1 offset0:40 offset1:42
	v_add_f32_e32 v1, v172, v108
	v_add_f32_e32 v107, v172, v109
	ds_write2st64_b32 v141, v1, v107 offset0:44 offset1:46
	v_add_f32_e32 v1, v172, v160
	v_add_f32_e32 v107, v172, v161
	ds_write2st64_b32 v141, v1, v107 offset0:48 offset1:50
	v_add_f32_e32 v1, v172, v162
	v_add_f32_e32 v107, v172, v163
	ds_write2st64_b32 v141, v1, v107 offset0:52 offset1:54
	s_waitcnt lgkmcnt(0)
	s_barrier
	s_and_saveexec_b64 s[50:51], s[4:5]
	s_cbranch_execz .LBB0_504
	ds_read_b32 v1, v127 offset:38400
	v_lshl_add_u32 v107, s79, 9, v127
	s_waitcnt lgkmcnt(0)
	ds_write_b32 v107, v1 offset:4096

.LBB0_580:
	s_add_u32 s0, s50, s38
	s_addc_u32 s1, s51, s39
	s_add_u32 s60, s48, s38
	s_addc_u32 s61, s49, s39
	s_add_u32 s31, s60, s46
	s_addc_u32 s44, s61, 0
	s_add_u32 s62, s31, 0x16e40800
	s_addc_u32 s63, s44, 0
	s_and_b32 s59, s58, 1
	s_cmp_eq_u32 s59, 0
	s_cselect_b64 s[44:45], -1, 0
	s_and_b64 s[64:65], s[44:45], exec
	s_cselect_b32 s31, 0xf0, s54
	v_add3_u32 v136, s31, v171, v170
	ds_read2_b32 v[72:73], v136 offset1:4
	v_lshl_add_u64 v[74:75], s[0:1], 0, v[102:103]
	ds_read2_b32 v[80:81], v136 offset0:64 offset1:68
	global_load_dwordx4 v[92:95], v[74:75], off
	global_load_dwordx4 v[96:99], v[74:75], off offset:1024
	ds_read2_b32 v[132:133], v136 offset0:8 offset1:12
	v_lshl_add_u64 v[82:83], s[62:63], 0, v[104:105]
	s_waitcnt lgkmcnt(2)
	v_mfma_f32_16x16x4_f32 v[68:71], v72, v155, 0
	v_add_co_u32_e64 v72, s[0:1], s52, v74
	v_mfma_f32_16x16x4_f32 v[68:71], v73, v164, v[68:71]
	s_nop 0
	v_addc_co_u32_e64 v73, s[0:1], 0, v75, s[0:1]
	global_load_dwordx4 v[84:87], v[72:73], off
	global_load_dwordx4 v[88:91], v[72:73], off offset:1024
	v_add_co_u32_e64 v72, s[0:1], s47, v82
	s_nop 1
	v_addc_co_u32_e64 v73, s[0:1], 0, v83, s[0:1]
	s_waitcnt lgkmcnt(0)
	v_mfma_f32_16x16x4_f32 v[124:127], v132, v165, v[68:71]
	v_add_co_u32_e64 v134, s[0:1], s52, v82
	global_load_dwordx4 v[68:71], v[82:83], off
	s_nop 0
	global_load_dwordx4 v[72:75], v[72:73], off
	v_addc_co_u32_e64 v135, s[0:1], 0, v83, s[0:1]
	v_mfma_f32_16x16x4_f32 v[76:79], v80, v155, 0
	v_add_co_u32_e64 v80, s[0:1], s53, v82
	v_mfma_f32_16x16x4_f32 v[124:127], v133, v166, v[124:127]
	v_mfma_f32_16x16x4_f32 v[128:131], v81, v164, v[76:79]
	v_addc_co_u32_e64 v81, s[0:1], 0, v83, s[0:1]
	s_nop 5
	global_load_dwordx4 v[76:79], v[134:135], off
	s_nop 0
	global_load_dwordx4 v[80:83], v[80:81], off
	ds_read2_b32 v[134:135], v136 offset0:72 offset1:76
	v_add_f32_e32 v124, v167, v124
	v_min_f32_e32 v137, 0, v124
	v_mul_f32_e64 v124, |v124|, s55
	v_exp_f32_e32 v124, v124
	v_add_f32_e32 v126, v167, v126
	v_mul_f32_e64 v133, |v126|, s55
	v_exp_f32_e32 v133, v133
	v_add_f32_e32 v124, 1.0, v124
	v_log_f32_e32 v124, v124
	s_waitcnt lgkmcnt(0)
	v_mfma_f32_16x16x4_f32 v[128:131], v134, v165, v[128:131]
	v_add_f32_e32 v133, 1.0, v133
	v_min_f32_e32 v139, 0, v126
	v_fmac_f32_e32 v137, 0xbf317218, v124
	v_log_f32_e32 v124, v133
	v_add_f32_e32 v134, v167, v127
	v_add_f32_e32 v125, v167, v125
	v_mul_f32_e64 v132, |v125|, s55
	v_fmac_f32_e32 v139, 0xbf317218, v124
	v_mul_f32_e64 v124, |v134|, s55
	v_min_f32_e32 v138, 0, v125
	v_exp_f32_e32 v140, v124
	v_mfma_f32_16x16x4_f32 v[124:127], v135, v166, v[128:131]
	v_exp_f32_e32 v132, v132
	v_add_f32_e32 v129, 1.0, v140
	v_log_f32_e32 v129, v129
	v_add_f32_e32 v132, 1.0, v132
	v_log_f32_e32 v132, v132
	v_min_f32_e32 v140, 0, v134
	s_nop 3
	v_add_f32_e32 v124, v167, v124
	v_mul_f32_e64 v128, |v124|, s55
	v_fmac_f32_e32 v138, 0xbf317218, v132
	v_exp_f32_e32 v128, v128
	ds_read2_b32 v[132:133], v136 offset0:128 offset1:132
	v_min_f32_e32 v141, 0, v124
	v_fmac_f32_e32 v140, 0xbf317218, v129
	v_add_f32_e32 v128, 1.0, v128
	v_log_f32_e32 v128, v128
	ds_read2_b32 v[134:135], v136 offset0:136 offset1:140
	v_add_f32_e32 v124, v167, v125
	v_mul_f32_e64 v125, |v124|, s55
	v_fmac_f32_e32 v141, 0xbf317218, v128
	s_waitcnt lgkmcnt(1)
	v_mfma_f32_16x16x4_f32 v[128:131], v132, v155, 0
	v_add_f32_e32 v132, v167, v126
	v_exp_f32_e32 v125, v125
	v_mul_f32_e64 v126, |v132|, s55
	v_exp_f32_e32 v126, v126
	v_min_f32_e32 v142, 0, v124
	v_add_f32_e32 v124, 1.0, v125
	v_add_f32_e32 v144, v167, v127
	v_mfma_f32_16x16x4_f32 v[128:131], v133, v164, v[128:131]
	v_log_f32_e32 v133, v124
	v_add_f32_e32 v124, 1.0, v126
	v_log_f32_e32 v143, v124
	v_mul_f32_e64 v145, |v144|, s55
	v_fmac_f32_e32 v142, 0xbf317218, v133
	s_waitcnt lgkmcnt(0)
	v_mfma_f32_16x16x4_f32 v[124:127], v134, v165, v[128:131]
	s_nop 2
	v_exp_f32_e32 v128, v145
	v_min_f32_e32 v145, 0, v132
	ds_read2_b32 v[132:133], v136 offset0:192 offset1:196
	v_fmac_f32_e32 v145, 0xbf317218, v143
	v_add_f32_e32 v128, 1.0, v128
	v_log_f32_e32 v128, v128
	v_min_f32_e32 v143, 0, v144
	v_mfma_f32_16x16x4_f32 v[124:127], v135, v166, v[124:127]
	v_fmac_f32_e32 v143, 0xbf317218, v128
	s_nop 8
	v_add_f32_e32 v124, v167, v124
	v_mul_f32_e64 v128, |v124|, s55
	v_exp_f32_e32 v134, v128
	s_waitcnt lgkmcnt(0)
	v_mfma_f32_16x16x4_f32 v[128:131], v132, v155, 0
	v_add_f32_e32 v125, v167, v125
	v_mul_f32_e64 v135, |v125|, s55
	v_exp_f32_e32 v132, v135
	v_min_f32_e32 v144, 0, v124
	v_add_f32_e32 v124, 1.0, v134
	ds_read2_b32 v[134:135], v136 offset0:200 offset1:204
	v_add_f32_e32 v132, 1.0, v132
	v_mfma_f32_16x16x4_f32 v[128:131], v133, v164, v[128:131]
	v_log_f32_e32 v132, v132
	v_log_f32_e32 v124, v124
	v_min_f32_e32 v133, 0, v125
	v_add_f32_e32 v146, v167, v127
	v_fmac_f32_e32 v133, 0xbf317218, v132
	v_add_f32_e32 v132, v167, v126
	v_fmac_f32_e32 v144, 0xbf317218, v124
	v_mul_f32_e64 v124, |v132|, s55
	v_exp_f32_e32 v136, v124
	s_waitcnt lgkmcnt(0)
	v_mfma_f32_16x16x4_f32 v[124:127], v134, v165, v[128:131]
	v_mul_f32_e64 v128, |v146|, s55
	v_exp_f32_e32 v128, v128
	v_add_f32_e32 v130, 1.0, v136
	v_log_f32_e32 v130, v130
	v_min_f32_e32 v129, 0, v132
	v_add_f32_e32 v128, 1.0, v128
	v_log_f32_e32 v128, v128
	v_mfma_f32_16x16x4_f32 v[124:127], v135, v166, v[124:127]
	v_fmac_f32_e32 v129, 0xbf317218, v130
	v_min_f32_e32 v130, 0, v146
	v_fmac_f32_e32 v130, 0xbf317218, v128
	s_nop 6
	v_add_f32_e32 v124, v167, v124
	v_mul_f32_e64 v131, |v124|, s55
	v_exp_f32_e32 v131, v131
	v_add_f32_e32 v125, v167, v125
	v_min_f32_e32 v124, 0, v124
	v_add_f32_e32 v126, v167, v126
	v_add_f32_e32 v128, 1.0, v131
	v_mul_f32_e64 v131, |v125|, s55
	v_log_f32_e32 v128, v128
	v_exp_f32_e32 v131, v131
	v_add_f32_e32 v127, v167, v127
	v_mul_f32_e64 v132, |v127|, s55
	v_fmac_f32_e32 v124, 0xbf317218, v128
	v_add_f32_e32 v128, 1.0, v131
	v_mul_f32_e64 v131, |v126|, s55
	v_log_f32_e32 v128, v128
	v_exp_f32_e32 v131, v131
	v_exp_f32_e32 v132, v132
	v_min_f32_e32 v125, 0, v125
	v_fmac_f32_e32 v125, 0xbf317218, v128
	v_add_f32_e32 v128, 1.0, v131
	v_add_f32_e32 v131, 1.0, v132
	v_log_f32_e32 v131, v131
	v_log_f32_e32 v128, v128
	v_min_f32_e32 v127, 0, v127
	v_min_f32_e32 v126, 0, v126
	v_fmac_f32_e32 v127, 0xbf317218, v131
	v_fmac_f32_e32 v126, 0xbf317218, v128
	v_fma_f32 v127, v127, s56, 0
	v_fmamk_f32 v126, v126, 0x3d800000, v127
	v_fmamk_f32 v125, v125, 0x3d800000, v126
	v_fmamk_f32 v124, v124, 0x3d800000, v125
	v_fmamk_f32 v128, v130, 0x3d800000, v124
	v_fmamk_f32 v129, v129, 0x3d800000, v128
	v_fmamk_f32 v130, v133, 0x3d800000, v129
	v_fmamk_f32 v131, v144, 0x3d800000, v130
	v_fmamk_f32 v132, v143, 0x3d800000, v131
	v_fmamk_f32 v133, v145, 0x3d800000, v132
	v_fmamk_f32 v134, v142, 0x3d800000, v133
	v_fmamk_f32 v135, v141, 0x3d800000, v134
	v_fmamk_f32 v136, v140, 0x3d800000, v135
	v_fmamk_f32 v139, v139, 0x3d800000, v136
	v_fmamk_f32 v138, v138, 0x3d800000, v139
	v_fmamk_f32 v137, v137, 0x3d800000, v138
	v_mov_b32_e32 v252, v137
	v_mov_b32_e32 v253, v137
	s_nop 1
	v_permlane16_swap_b32_e32 v252, v253
	v_mov_b32_e32 v254, v252
	v_mov_b32_e32 v255, v253
	s_nop 1
	v_permlane32_swap_b32_e32 v252, v254
	v_permlane32_swap_b32_e32 v253, v255
	v_mov_b32_e32 v140, v255
	v_mov_b32_e32 v141, v254
	v_mov_b32_e32 v142, v253
	s_waitcnt lgkmcnt(2)
	v_cndmask_b32_e64 v140, v140, 0, s[2:3]
	s_waitcnt lgkmcnt(1)
	v_cndmask_b32_e64 v141, 0, v141, s[4:5]
	v_add_f32_e32 v140, v141, v140
	s_waitcnt lgkmcnt(0)
	v_cndmask_b32_e64 v141, 0, v142, s[6:7]
	v_add_f32_e32 v140, v141, v140
	v_add_f32_e32 v137, v140, v137
	v_add_f32_e32 v138, v140, v138
	v_add_f32_e32 v124, v140, v124
	v_add_f32_e32 v125, v140, v125
	ds_write2st64_b32 v184, v137, v138 offset0:24 offset1:26
	v_add_f32_e32 v137, v140, v139
	v_add_f32_e32 v136, v140, v136
	v_add_f32_e32 v135, v140, v135
	v_add_f32_e32 v134, v140, v134
	v_add_f32_e32 v133, v140, v133
	v_add_f32_e32 v132, v140, v132
	v_add_f32_e32 v131, v140, v131
	v_add_f32_e32 v130, v140, v130
	v_add_f32_e32 v129, v140, v129
	v_add_f32_e32 v128, v140, v128
	ds_write2st64_b32 v184, v124, v125 offset0:48 offset1:50
	v_add_f32_e32 v124, v140, v126
	v_add_f32_e32 v125, v140, v127
	ds_write2st64_b32 v184, v137, v136 offset0:28 offset1:30
	ds_write2st64_b32 v184, v135, v134 offset0:32 offset1:34
	ds_write2st64_b32 v184, v133, v132 offset0:36 offset1:38
	ds_write2st64_b32 v184, v131, v130 offset0:40 offset1:42
	ds_write2st64_b32 v184, v129, v128 offset0:44 offset1:46
	ds_write2st64_b32 v184, v124, v125 offset0:52 offset1:54
	s_waitcnt lgkmcnt(0)
	s_barrier
	s_and_saveexec_b64 s[0:1], s[8:9]
	s_cbranch_execz .LBB0_582
	ds_read_b32 v124, v175 offset:6144
	v_lshl_add_u32 v125, s59, 9, v175
	s_waitcnt lgkmcnt(0)
	ds_write_b32 v125, v124 offset:4096

.LBB0_664:
	s_add_u32 s62, s61, s76
	s_addc_u32 s63, s91, s77
	v_lshl_add_u64 v[70:71], s[62:63], 0, v[112:113]
	s_add_u32 s62, s55, s76
	s_addc_u32 s63, s57, s77
	s_add_u32 s62, s62, s68
	v_add_co_u32_e32 v74, vcc, s95, v70
	s_addc_u32 s63, s63, 0
	s_nop 0
	v_addc_co_u32_e32 v75, vcc, 0, v71, vcc
	v_lshl_add_u64 v[86:87], s[62:63], 0, v[114:115]
	v_add_co_u32_e32 v78, vcc, s81, v86
	s_and_b32 s93, s92, 1
	s_add_i32 s69, s66, 0xf0
	v_addc_co_u32_e32 v79, vcc, 0, v87, vcc
	s_cmp_eq_u32 s93, 0
	v_add_co_u32_e32 v82, vcc, s95, v86
	s_cselect_b64 s[78:79], -1, 0
	s_nop 0
	v_addc_co_u32_e32 v83, vcc, 0, v87, vcc
	s_and_b64 s[62:63], s[78:79], exec
	global_load_dwordx4 v[94:97], v[70:71], off
	global_load_dwordx4 v[98:101], v[70:71], off offset:1024
	s_nop 0
	global_load_dwordx4 v[70:73], v[74:75], off
	global_load_dwordx4 v[90:93], v[74:75], off offset:1024
	s_cselect_b32 s62, 0xf0, s69
	global_load_dwordx4 v[74:77], v[86:87], off
	v_add_co_u32_e32 v86, vcc, s96, v86
	v_add3_u32 v137, s62, v177, v175
	s_nop 0
	v_addc_co_u32_e32 v87, vcc, 0, v87, vcc
	global_load_dwordx4 v[78:81], v[78:79], off
	s_nop 0
	global_load_dwordx4 v[82:85], v[82:83], off
	s_nop 0
	global_load_dwordx4 v[86:89], v[86:87], off
	ds_read2_b32 v[134:135], v137 offset1:4
	ds_read2_b32 v[142:143], v137 offset0:8 offset1:12
	s_waitcnt lgkmcnt(1)
	v_mfma_f32_16x16x4_f32 v[138:141], v134, v104, 0
	ds_read2_b32 v[146:147], v137 offset0:128 offset1:132
	v_mfma_f32_16x16x4_f32 v[138:141], v135, v105, v[138:141]
	s_waitcnt lgkmcnt(1)
	v_mfma_f32_16x16x4_f32 v[138:141], v142, v106, v[138:141]
	v_mfma_f32_16x16x4_f32 v[138:141], v143, v107, v[138:141]
	ds_read2_b32 v[142:143], v137 offset0:64 offset1:68
	s_nop 8
	v_add_f32_e32 v134, v108, v138
	v_min_f32_e32 v109, 0, v134
	v_mul_f32_e64 v134, |v134|, s97
	v_exp_f32_e32 v134, v134
	v_add_f32_e32 v135, v108, v139
	v_add_f32_e32 v136, v108, v140
	v_add_f32_e32 v138, v108, v141
	v_add_f32_e32 v134, 1.0, v134
	v_log_f32_e32 v134, v134
	s_nop 0
	v_fmac_f32_e32 v109, 0xbf317218, v134
	v_min_f32_e32 v134, 0, v135
	v_mul_f32_e64 v135, |v135|, s97
	v_exp_f32_e32 v135, v135
	v_fma_f32 v109, v109, s0, 0
	v_add_f32_e32 v135, 1.0, v135
	v_log_f32_e32 v135, v135
	s_nop 0
	v_fmac_f32_e32 v134, 0xbf317218, v135
	v_min_f32_e32 v135, 0, v136
	v_mul_f32_e64 v136, |v136|, s97
	v_exp_f32_e32 v136, v136
	v_fmamk_f32 v134, v134, 0x3d800000, v109
	v_add_f32_e32 v136, 1.0, v136
	v_log_f32_e32 v136, v136
	s_nop 0
	v_fmac_f32_e32 v135, 0xbf317218, v136
	v_min_f32_e32 v136, 0, v138
	v_mul_f32_e64 v138, |v138|, s97
	v_exp_f32_e32 v138, v138
	v_fmamk_f32 v135, v135, 0x3d800000, v134
	v_add_f32_e32 v138, 1.0, v138
	v_log_f32_e32 v138, v138
	s_nop 0
	v_fmac_f32_e32 v136, 0xbf317218, v138
	s_waitcnt lgkmcnt(0)
	v_mfma_f32_16x16x4_f32 v[138:141], v142, v104, 0
	v_fmamk_f32 v136, v136, 0x3d800000, v135
	v_mfma_f32_16x16x4_f32 v[138:141], v143, v105, v[138:141]
	ds_read2_b32 v[142:143], v137 offset0:72 offset1:76
	s_waitcnt lgkmcnt(0)
	v_mfma_f32_16x16x4_f32 v[138:141], v142, v106, v[138:141]
	v_mfma_f32_16x16x4_f32 v[138:141], v143, v107, v[138:141]
	s_nop 9
	v_add_f32_e32 v142, v108, v138
	v_min_f32_e32 v138, 0, v142
	v_mul_f32_e64 v142, |v142|, s97
	v_exp_f32_e32 v142, v142
	s_nop 0
	v_add_f32_e32 v142, 1.0, v142
	v_log_f32_e32 v142, v142
	s_nop 0
	v_fmac_f32_e32 v138, 0xbf317218, v142
	v_add_f32_e32 v142, v108, v139
	v_min_f32_e32 v139, 0, v142
	v_mul_f32_e64 v142, |v142|, s97
	v_exp_f32_e32 v142, v142
	s_nop 0
	v_add_f32_e32 v142, 1.0, v142
	v_log_f32_e32 v142, v142
	s_nop 0
	v_fmac_f32_e32 v139, 0xbf317218, v142
	v_add_f32_e32 v142, v108, v140
	v_min_f32_e32 v140, 0, v142
	v_mul_f32_e64 v142, |v142|, s97
	v_exp_f32_e32 v142, v142
	s_nop 0
	v_add_f32_e32 v142, 1.0, v142
	v_log_f32_e32 v142, v142
	s_nop 0
	v_fmac_f32_e32 v140, 0xbf317218, v142
	v_add_f32_e32 v142, v108, v141
	v_min_f32_e32 v141, 0, v142
	v_mul_f32_e64 v142, |v142|, s97
	v_exp_f32_e32 v142, v142
	s_nop 0
	v_add_f32_e32 v142, 1.0, v142
	v_log_f32_e32 v142, v142
	s_nop 0
	v_fmac_f32_e32 v141, 0xbf317218, v142
	v_mfma_f32_16x16x4_f32 v[142:145], v146, v104, 0
	v_mfma_f32_16x16x4_f32 v[142:145], v147, v105, v[142:145]
	ds_read2_b32 v[146:147], v137 offset0:136 offset1:140
	s_waitcnt lgkmcnt(0)
	v_mfma_f32_16x16x4_f32 v[142:145], v146, v106, v[142:145]
	v_mfma_f32_16x16x4_f32 v[142:145], v147, v107, v[142:145]
	ds_read2_b32 v[146:147], v137 offset0:192 offset1:196
	s_nop 8
	v_add_f32_e32 v142, v108, v142
	v_min_f32_e32 v148, 0, v142
	v_mul_f32_e64 v142, |v142|, s97
	v_exp_f32_e32 v142, v142
	s_nop 0
	v_add_f32_e32 v142, 1.0, v142
	v_log_f32_e32 v142, v142
	s_nop 0
	v_fmac_f32_e32 v148, 0xbf317218, v142
	v_add_f32_e32 v142, v108, v143
	v_min_f32_e32 v149, 0, v142
	v_mul_f32_e64 v142, |v142|, s97
	v_exp_f32_e32 v142, v142
	s_nop 0
	v_add_f32_e32 v142, 1.0, v142
	v_log_f32_e32 v142, v142
	s_nop 0
	v_fmac_f32_e32 v149, 0xbf317218, v142
	v_add_f32_e32 v142, v108, v144
	v_min_f32_e32 v150, 0, v142
	v_mul_f32_e64 v142, |v142|, s97
	v_exp_f32_e32 v142, v142
	s_nop 0
	v_add_f32_e32 v142, 1.0, v142
	v_log_f32_e32 v142, v142
	s_nop 0
	v_fmac_f32_e32 v150, 0xbf317218, v142
	v_add_f32_e32 v142, v108, v145
	v_min_f32_e32 v151, 0, v142
	v_mul_f32_e64 v142, |v142|, s97
	v_exp_f32_e32 v142, v142
	s_nop 0
	v_add_f32_e32 v142, 1.0, v142
	v_log_f32_e32 v142, v142
	s_nop 0
	v_fmac_f32_e32 v151, 0xbf317218, v142
	s_waitcnt lgkmcnt(0)
	v_mfma_f32_16x16x4_f32 v[142:145], v146, v104, 0
	v_mfma_f32_16x16x4_f32 v[142:145], v147, v105, v[142:145]
	ds_read2_b32 v[146:147], v137 offset0:200 offset1:204
	s_waitcnt lgkmcnt(0)
	v_mfma_f32_16x16x4_f32 v[142:145], v146, v106, v[142:145]
	v_mfma_f32_16x16x4_f32 v[142:145], v147, v107, v[142:145]
	s_nop 9
	v_add_f32_e32 v137, v108, v142
	v_min_f32_e32 v142, 0, v137
	v_mul_f32_e64 v137, |v137|, s97
	v_exp_f32_e32 v137, v137
	s_nop 0
	v_add_f32_e32 v137, 1.0, v137
	v_log_f32_e32 v137, v137
	s_nop 0
	v_fmac_f32_e32 v142, 0xbf317218, v137
	v_add_f32_e32 v137, v108, v143
	v_min_f32_e32 v143, 0, v137
	v_mul_f32_e64 v137, |v137|, s97
	v_exp_f32_e32 v137, v137
	s_nop 0
	v_add_f32_e32 v137, 1.0, v137
	v_log_f32_e32 v137, v137
	s_nop 0
	v_fmac_f32_e32 v143, 0xbf317218, v137
	v_add_f32_e32 v137, v108, v144
	v_min_f32_e32 v144, 0, v137
	v_mul_f32_e64 v137, |v137|, s97
	v_exp_f32_e32 v137, v137
	s_nop 0
	v_add_f32_e32 v137, 1.0, v137
	v_log_f32_e32 v137, v137
	s_nop 0
	v_fmac_f32_e32 v144, 0xbf317218, v137
	v_add_f32_e32 v137, v108, v145
	v_min_f32_e32 v145, 0, v137
	v_mul_f32_e64 v137, |v137|, s97
	v_exp_f32_e32 v137, v137
	s_nop 0
	v_add_f32_e32 v137, 1.0, v137
	v_log_f32_e32 v137, v137
	s_nop 0
	v_fmac_f32_e32 v145, 0xbf317218, v137
	v_fmamk_f32 v137, v138, 0x3d800000, v136
	v_fmamk_f32 v138, v139, 0x3d800000, v137
	v_fmamk_f32 v139, v140, 0x3d800000, v138
	v_fmamk_f32 v140, v141, 0x3d800000, v139
	v_fmamk_f32 v141, v148, 0x3d800000, v140
	v_fmamk_f32 v146, v149, 0x3d800000, v141
	v_fmamk_f32 v147, v150, 0x3d800000, v146
	v_fmamk_f32 v148, v151, 0x3d800000, v147
	v_fmamk_f32 v142, v142, 0x3d800000, v148
	v_fmamk_f32 v143, v143, 0x3d800000, v142
	v_fmamk_f32 v144, v144, 0x3d800000, v143
	v_fmamk_f32 v145, v145, 0x3d800000, v144
	v_mov_b32_e32 v252, v145
	v_mov_b32_e32 v253, v145
	s_nop 1
	v_permlane16_swap_b32_e32 v252, v253
	v_mov_b32_e32 v254, v252
	v_mov_b32_e32 v255, v253
	s_nop 1
	v_permlane32_swap_b32_e32 v252, v254
	v_permlane32_swap_b32_e32 v253, v255
	v_mov_b32_e32 v149, v252
	v_mov_b32_e32 v150, v253
	v_mov_b32_e32 v151, v254
	s_waitcnt lgkmcnt(2)
	v_cndmask_b32_e64 v149, v149, 0, s[4:5]
	s_waitcnt lgkmcnt(1)
	v_cndmask_b32_e64 v150, 0, v150, s[6:7]
	v_add_f32_e32 v149, v149, v150
	s_waitcnt lgkmcnt(0)
	v_cndmask_b32_e64 v150, 0, v151, s[8:9]
	v_add_f32_e32 v149, v149, v150
	v_add_f32_e32 v109, v109, v149
	v_add_f32_e32 v134, v134, v149
	ds_write2st64_b32 v200, v109, v134 offset0:24 offset1:26
	v_add_f32_e32 v109, v135, v149
	v_add_f32_e32 v134, v136, v149
	ds_write2st64_b32 v200, v109, v134 offset0:28 offset1:30
	v_add_f32_e32 v109, v137, v149
	v_add_f32_e32 v134, v138, v149
	ds_write2st64_b32 v200, v109, v134 offset0:32 offset1:34
	v_add_f32_e32 v109, v139, v149
	v_add_f32_e32 v134, v140, v149
	ds_write2st64_b32 v200, v109, v134 offset0:36 offset1:38
	v_add_f32_e32 v109, v141, v149
	v_add_f32_e32 v134, v146, v149
	ds_write2st64_b32 v200, v109, v134 offset0:40 offset1:42
	v_add_f32_e32 v109, v149, v147
	v_add_f32_e32 v134, v149, v148
	ds_write2st64_b32 v200, v109, v134 offset0:44 offset1:46
	v_add_f32_e32 v109, v149, v142
	v_add_f32_e32 v134, v149, v143
	ds_write2st64_b32 v200, v109, v134 offset0:48 offset1:50
	v_add_f32_e32 v109, v149, v144
	v_add_f32_e32 v134, v149, v145
	ds_write2st64_b32 v200, v109, v134 offset0:52 offset1:54
	s_waitcnt lgkmcnt(0)
	s_barrier
	s_and_saveexec_b64 s[62:63], s[10:11]
	s_cbranch_execz .LBB0_666
	ds_read_b32 v109, v178 offset:38400
	v_lshl_add_u32 v134, s93, 9, v178
	s_waitcnt lgkmcnt(0)
	ds_write_b32 v134, v109 offset:4096

.LBB0_680:
	s_add_u32 s62, s71, s60
	s_addc_u32 s63, s74, s61
	s_add_u32 s72, s48, s60
	s_addc_u32 s73, s70, s61
	s_add_u32 s55, s72, s68
	v_lshl_add_u64 v[70:71], s[62:63], 0, v[112:113]
	s_addc_u32 s63, s73, 0
	s_add_u32 s62, s55, 0xafc0800
	v_add_co_u32_e32 v74, vcc, s95, v70
	s_addc_u32 s63, s63, 0
	s_nop 0
	v_addc_co_u32_e32 v75, vcc, 0, v71, vcc
	v_lshl_add_u64 v[86:87], s[62:63], 0, v[114:115]
	v_add_co_u32_e32 v78, vcc, s81, v86
	s_and_b32 s67, s75, 1
	s_nop 0
	v_addc_co_u32_e32 v79, vcc, 0, v87, vcc
	s_cmp_eq_u32 s67, 0
	v_add_co_u32_e32 v82, vcc, s95, v86
	s_cselect_b64 s[64:65], -1, 0
	s_nop 0
	v_addc_co_u32_e32 v83, vcc, 0, v87, vcc
	s_and_b64 s[62:63], s[64:65], exec
	global_load_dwordx4 v[94:97], v[70:71], off
	global_load_dwordx4 v[98:101], v[70:71], off offset:1024
	s_nop 0
	global_load_dwordx4 v[70:73], v[74:75], off
	global_load_dwordx4 v[90:93], v[74:75], off offset:1024
	s_cselect_b32 s55, 0xf0, s69
	global_load_dwordx4 v[74:77], v[86:87], off
	v_add_co_u32_e32 v86, vcc, s96, v86
	v_add3_u32 v105, s55, v177, v175
	s_nop 0
	v_addc_co_u32_e32 v87, vcc, 0, v87, vcc
	global_load_dwordx4 v[78:81], v[78:79], off
	s_nop 0
	global_load_dwordx4 v[82:85], v[82:83], off
	s_nop 0
	global_load_dwordx4 v[86:89], v[86:87], off
	ds_read2_b32 v[102:103], v105 offset1:4
	ds_read2_b32 v[136:137], v105 offset0:8 offset1:12
	s_waitcnt vmcnt(12) lgkmcnt(1)
	v_mfma_f32_16x16x4_f32 v[106:109], v102, v219, 0
	ds_read2_b32 v[140:141], v105 offset0:128 offset1:132
	s_waitcnt vmcnt(11)
	v_mfma_f32_16x16x4_f32 v[106:109], v103, v220, v[106:109]
	s_waitcnt vmcnt(10) lgkmcnt(1)
	v_mfma_f32_16x16x4_f32 v[106:109], v136, v221, v[106:109]
	s_waitcnt vmcnt(9)
	v_mfma_f32_16x16x4_f32 v[106:109], v137, v222, v[106:109]
	ds_read2_b32 v[136:137], v105 offset0:64 offset1:68
	s_waitcnt vmcnt(8)
	s_nop 7
	v_add_f32_e32 v102, v223, v106
	v_min_f32_e32 v0, 0, v102
	v_mul_f32_e64 v102, |v102|, s97
	v_exp_f32_e32 v102, v102
	v_add_f32_e32 v103, v223, v107
	v_add_f32_e32 v104, v223, v108
	v_add_f32_e32 v106, v223, v109
	v_add_f32_e32 v102, 1.0, v102
	v_log_f32_e32 v102, v102
	s_nop 0
	v_fmac_f32_e32 v0, 0xbf317218, v102
	v_min_f32_e32 v102, 0, v103
	v_mul_f32_e64 v103, |v103|, s97
	v_exp_f32_e32 v103, v103
	s_nop 0
	v_add_f32_e32 v103, 1.0, v103
	v_log_f32_e32 v103, v103
	s_nop 0
	v_fmac_f32_e32 v102, 0xbf317218, v103
	v_min_f32_e32 v103, 0, v104
	v_mul_f32_e64 v104, |v104|, s97
	v_exp_f32_e32 v104, v104
	s_nop 0
	v_add_f32_e32 v104, 1.0, v104
	v_log_f32_e32 v104, v104
	s_nop 0
	v_fmac_f32_e32 v103, 0xbf317218, v104
	v_min_f32_e32 v104, 0, v106
	v_mul_f32_e64 v106, |v106|, s97
	v_exp_f32_e32 v106, v106
	s_nop 0
	v_add_f32_e32 v106, 1.0, v106
	v_log_f32_e32 v106, v106
	s_nop 0
	v_fmac_f32_e32 v104, 0xbf317218, v106
	s_waitcnt lgkmcnt(0)
	v_mfma_f32_16x16x4_f32 v[106:109], v136, v219, 0
	v_mfma_f32_16x16x4_f32 v[106:109], v137, v220, v[106:109]
	ds_read2_b32 v[136:137], v105 offset0:72 offset1:76
	s_waitcnt lgkmcnt(0)
	v_mfma_f32_16x16x4_f32 v[106:109], v136, v221, v[106:109]
	v_mfma_f32_16x16x4_f32 v[106:109], v137, v222, v[106:109]
	s_nop 9
	v_add_f32_e32 v136, v223, v106
	v_min_f32_e32 v106, 0, v136
	v_mul_f32_e64 v136, |v136|, s97
	v_exp_f32_e32 v136, v136
	s_nop 0
	v_add_f32_e32 v136, 1.0, v136
	v_log_f32_e32 v136, v136
	s_nop 0
	v_fmac_f32_e32 v106, 0xbf317218, v136
	v_add_f32_e32 v136, v223, v107
	v_min_f32_e32 v107, 0, v136
	v_mul_f32_e64 v136, |v136|, s97
	v_exp_f32_e32 v136, v136
	s_nop 0
	v_add_f32_e32 v136, 1.0, v136
	v_log_f32_e32 v136, v136
	s_nop 0
	v_fmac_f32_e32 v107, 0xbf317218, v136
	v_add_f32_e32 v136, v223, v108
	v_min_f32_e32 v108, 0, v136
	v_mul_f32_e64 v136, |v136|, s97
	v_exp_f32_e32 v136, v136
	s_nop 0
	v_add_f32_e32 v136, 1.0, v136
	v_log_f32_e32 v136, v136
	s_nop 0
	v_fmac_f32_e32 v108, 0xbf317218, v136
	v_add_f32_e32 v136, v223, v109
	v_min_f32_e32 v109, 0, v136
	v_mul_f32_e64 v136, |v136|, s97
	v_exp_f32_e32 v136, v136
	s_nop 0
	v_add_f32_e32 v136, 1.0, v136
	v_log_f32_e32 v136, v136
	s_nop 0
	v_fmac_f32_e32 v109, 0xbf317218, v136
	v_mfma_f32_16x16x4_f32 v[136:139], v140, v219, 0
	v_mfma_f32_16x16x4_f32 v[136:139], v141, v220, v[136:139]
	ds_read2_b32 v[140:141], v105 offset0:136 offset1:140
	s_waitcnt lgkmcnt(0)
	v_mfma_f32_16x16x4_f32 v[136:139], v140, v221, v[136:139]
	v_mfma_f32_16x16x4_f32 v[136:139], v141, v222, v[136:139]
	ds_read2_b32 v[140:141], v105 offset0:192 offset1:196
	s_nop 8
	v_add_f32_e32 v136, v223, v136
	v_min_f32_e32 v142, 0, v136
	v_mul_f32_e64 v136, |v136|, s97
	v_exp_f32_e32 v136, v136
	s_nop 0
	v_add_f32_e32 v136, 1.0, v136
	v_log_f32_e32 v136, v136
	s_nop 0
	v_fmac_f32_e32 v142, 0xbf317218, v136
	v_add_f32_e32 v136, v223, v137
	v_min_f32_e32 v143, 0, v136
	v_mul_f32_e64 v136, |v136|, s97
	v_exp_f32_e32 v136, v136
	s_nop 0
	v_add_f32_e32 v136, 1.0, v136
	v_log_f32_e32 v136, v136
	s_nop 0
	v_fmac_f32_e32 v143, 0xbf317218, v136
	v_add_f32_e32 v136, v223, v138
	v_min_f32_e32 v144, 0, v136
	v_mul_f32_e64 v136, |v136|, s97
	v_exp_f32_e32 v136, v136
	s_nop 0
	v_add_f32_e32 v136, 1.0, v136
	v_log_f32_e32 v136, v136
	s_nop 0
	v_fmac_f32_e32 v144, 0xbf317218, v136
	v_add_f32_e32 v136, v223, v139
	v_min_f32_e32 v145, 0, v136
	v_mul_f32_e64 v136, |v136|, s97
	v_exp_f32_e32 v136, v136
	s_nop 0
	v_add_f32_e32 v136, 1.0, v136
	v_log_f32_e32 v136, v136
	s_nop 0
	v_fmac_f32_e32 v145, 0xbf317218, v136
	s_waitcnt lgkmcnt(0)
	v_mfma_f32_16x16x4_f32 v[136:139], v140, v219, 0
	v_mfma_f32_16x16x4_f32 v[136:139], v141, v220, v[136:139]
	ds_read2_b32 v[140:141], v105 offset0:200 offset1:204
	s_waitcnt lgkmcnt(0)
	v_mfma_f32_16x16x4_f32 v[136:139], v140, v221, v[136:139]
	v_mfma_f32_16x16x4_f32 v[136:139], v141, v222, v[136:139]
	s_nop 9
	v_add_f32_e32 v105, v223, v136
	v_min_f32_e32 v136, 0, v105
	v_mul_f32_e64 v105, |v105|, s97
	v_exp_f32_e32 v105, v105
	s_nop 0
	v_add_f32_e32 v105, 1.0, v105
	v_log_f32_e32 v105, v105
	s_nop 0
	v_fmac_f32_e32 v136, 0xbf317218, v105
	v_add_f32_e32 v105, v223, v137
	v_min_f32_e32 v137, 0, v105
	v_mul_f32_e64 v105, |v105|, s97
	v_exp_f32_e32 v105, v105
	s_nop 0
	v_add_f32_e32 v105, 1.0, v105
	v_log_f32_e32 v105, v105
	s_nop 0
	v_fmac_f32_e32 v137, 0xbf317218, v105
	v_add_f32_e32 v105, v223, v138
	v_min_f32_e32 v138, 0, v105
	v_mul_f32_e64 v105, |v105|, s97
	v_exp_f32_e32 v105, v105
	s_nop 0
	v_add_f32_e32 v105, 1.0, v105
	v_log_f32_e32 v105, v105
	s_nop 0
	v_fmac_f32_e32 v138, 0xbf317218, v105
	v_add_f32_e32 v105, v223, v139
	v_min_f32_e32 v139, 0, v105
	v_mul_f32_e64 v105, |v105|, s97
	v_exp_f32_e32 v105, v105
	s_nop 0
	v_add_f32_e32 v105, 1.0, v105
	v_log_f32_e32 v105, v105
	s_nop 0
	v_fmac_f32_e32 v139, 0xbf317218, v105
	v_fma_f32 v105, v139, s0, 0
	v_fmamk_f32 v138, v138, 0x3d800000, v105
	v_fmamk_f32 v137, v137, 0x3d800000, v138
	v_fmamk_f32 v136, v136, 0x3d800000, v137
	v_fmamk_f32 v139, v145, 0x3d800000, v136
	v_fmamk_f32 v140, v144, 0x3d800000, v139
	v_fmamk_f32 v141, v143, 0x3d800000, v140
	v_fmamk_f32 v142, v142, 0x3d800000, v141
	v_fmamk_f32 v109, v109, 0x3d800000, v142
	v_fmamk_f32 v108, v108, 0x3d800000, v109
	v_fmamk_f32 v107, v107, 0x3d800000, v108
	v_fmamk_f32 v106, v106, 0x3d800000, v107
	v_fmamk_f32 v104, v104, 0x3d800000, v106
	v_fmamk_f32 v103, v103, 0x3d800000, v104
	v_fmamk_f32 v102, v102, 0x3d800000, v103
	v_fmamk_f32 v0, v0, 0x3d800000, v102
	v_mov_b32_e32 v252, v0
	v_mov_b32_e32 v253, v0
	s_nop 1
	v_permlane16_swap_b32_e32 v252, v253
	v_mov_b32_e32 v254, v252
	v_mov_b32_e32 v255, v253
	s_nop 1
	v_permlane32_swap_b32_e32 v252, v254
	v_permlane32_swap_b32_e32 v253, v255
	v_mov_b32_e32 v144, v254
	v_mov_b32_e32 v145, v255
	v_mov_b32_e32 v143, v253
	s_waitcnt lgkmcnt(2)
	v_cndmask_b32_e64 v144, 0, v144, s[28:29]
	s_waitcnt lgkmcnt(1)
	v_cndmask_b32_e64 v145, v145, 0, s[8:9]
	v_add_f32_e32 v144, v144, v145
	s_waitcnt lgkmcnt(0)
	v_cndmask_b32_e64 v143, 0, v143, s[4:5]
	v_add_f32_e32 v143, v143, v144
	v_add_f32_e32 v0, v143, v0
	v_add_f32_e32 v102, v143, v102
	ds_write2st64_b32 v200, v0, v102 offset0:24 offset1:26
	v_add_f32_e32 v0, v143, v103
	v_add_f32_e32 v102, v143, v104
	ds_write2st64_b32 v200, v0, v102 offset0:28 offset1:30
	v_add_f32_e32 v0, v143, v106
	v_add_f32_e32 v102, v143, v107
	ds_write2st64_b32 v200, v0, v102 offset0:32 offset1:34
	v_add_f32_e32 v0, v143, v108
	v_add_f32_e32 v102, v143, v109
	ds_write2st64_b32 v200, v0, v102 offset0:36 offset1:38
	v_add_f32_e32 v0, v143, v142
	v_add_f32_e32 v102, v143, v141
	ds_write2st64_b32 v200, v0, v102 offset0:40 offset1:42
	v_add_f32_e32 v0, v143, v140
	v_add_f32_e32 v102, v143, v139
	ds_write2st64_b32 v200, v0, v102 offset0:44 offset1:46
	v_add_f32_e32 v0, v143, v136
	v_add_f32_e32 v102, v143, v137
	ds_write2st64_b32 v200, v0, v102 offset0:48 offset1:50
	v_add_f32_e32 v0, v143, v138
	v_add_f32_e32 v102, v143, v105
	ds_write2st64_b32 v200, v0, v102 offset0:52 offset1:54
	s_waitcnt lgkmcnt(0)
	s_barrier
	s_and_saveexec_b64 s[62:63], s[10:11]
	s_cbranch_execz .LBB0_682
	ds_read_b32 v0, v178 offset:6144
	v_lshl_add_u32 v102, s67, 9, v178
	s_waitcnt lgkmcnt(0)
	ds_write_b32 v102, v0 offset:4096

.LBB0_2090:
	v_mov_b32_e32 v252, v169
	v_mov_b32_e32 v253, v169
	s_nop 1
	v_permlane16_swap_b32_e32 v252, v253
	v_mov_b32_e32 v254, v252
	v_mov_b32_e32 v255, v253
	s_nop 1
	v_permlane32_swap_b32_e32 v252, v254
	v_permlane32_swap_b32_e32 v253, v255
	v_mov_b32_e32 v138, v252
	v_mov_b32_e32 v139, v253
	v_mov_b32_e32 v137, v254
	v_mov_b32_e32 v140, v255
	s_mov_b64 s[30:31], -1
	s_and_b64 vcc, exec, s[26:27]
	s_cbranch_vccz .LBB0_2092
	s_waitcnt lgkmcnt(0)
	v_cndmask_b32_e64 v136, v140, 0, s[6:7]
	v_cndmask_b32_e64 v140, 0, v137, s[8:9]
	v_add_f32_e32 v136, v140, v136
	v_cndmask_b32_e64 v140, 0, v139, s[10:11]
	v_add_f32_e32 v136, v140, v136
	s_mov_b64 s[30:31], 0

.LBB0_2105:
	v_mov_b32_e32 v252, v159
	v_mov_b32_e32 v253, v159
	s_nop 1
	v_permlane16_swap_b32_e32 v252, v253
	v_mov_b32_e32 v254, v252
	v_mov_b32_e32 v255, v253
	s_nop 1
	v_permlane32_swap_b32_e32 v252, v254
	v_permlane32_swap_b32_e32 v253, v255
	v_mov_b32_e32 v92, v252
	v_mov_b32_e32 v93, v253
	v_mov_b32_e32 v91, v254
	v_mov_b32_e32 v134, v255
	s_and_b64 vcc, exec, s[14:15]
	s_mov_b64 s[14:15], -1
	s_cbranch_vccnz .LBB0_2107
	s_waitcnt lgkmcnt(0)
	v_cndmask_b32_e64 v90, v134, 0, s[6:7]
	v_cndmask_b32_e64 v134, 0, v91, s[8:9]
	v_add_f32_e32 v90, v134, v90
	v_cndmask_b32_e64 v134, 0, v93, s[10:11]
	v_add_f32_e32 v90, v134, v90
	s_mov_b64 s[14:15], 0

.LBB0_2183:
	s_add_u32 s0, s48, s34
	s_addc_u32 s1, s49, s35
	s_add_u32 s58, s39, s34
	s_addc_u32 s59, s37, s35
	s_add_u32 s42, s58, s44
	s_addc_u32 s43, s59, 0
	s_add_u32 s60, s42, 0x16e40800
	s_addc_u32 s61, s43, 0
	s_and_b32 s57, s56, 1
	s_cmp_eq_u32 s57, 0
	s_cselect_b64 s[42:43], -1, 0
	s_and_b64 s[62:63], s[42:43], exec
	s_cselect_b32 s62, 0xf0, s52
	v_add3_u32 v136, s62, v171, v170
	ds_read2_b32 v[72:73], v136 offset1:4
	v_lshl_add_u64 v[74:75], s[0:1], 0, v[102:103]
	ds_read2_b32 v[80:81], v136 offset0:64 offset1:68
	global_load_dwordx4 v[92:95], v[74:75], off
	global_load_dwordx4 v[96:99], v[74:75], off offset:1024
	ds_read2_b32 v[132:133], v136 offset0:8 offset1:12
	v_lshl_add_u64 v[82:83], s[60:61], 0, v[104:105]
	s_waitcnt lgkmcnt(2)
	v_mfma_f32_16x16x4_f32 v[68:71], v72, v155, 0
	v_add_co_u32_e64 v72, s[0:1], s50, v74
	v_mfma_f32_16x16x4_f32 v[68:71], v73, v164, v[68:71]
	s_nop 0
	v_addc_co_u32_e64 v73, s[0:1], 0, v75, s[0:1]
	global_load_dwordx4 v[84:87], v[72:73], off
	global_load_dwordx4 v[88:91], v[72:73], off offset:1024
	v_add_co_u32_e64 v72, s[0:1], s45, v82
	s_nop 1
	v_addc_co_u32_e64 v73, s[0:1], 0, v83, s[0:1]
	s_waitcnt lgkmcnt(0)
	v_mfma_f32_16x16x4_f32 v[124:127], v132, v165, v[68:71]
	v_add_co_u32_e64 v134, s[0:1], s50, v82
	global_load_dwordx4 v[68:71], v[82:83], off
	s_nop 0
	global_load_dwordx4 v[72:75], v[72:73], off
	v_addc_co_u32_e64 v135, s[0:1], 0, v83, s[0:1]
	v_mfma_f32_16x16x4_f32 v[76:79], v80, v155, 0
	v_add_co_u32_e64 v80, s[0:1], s51, v82
	v_mfma_f32_16x16x4_f32 v[124:127], v133, v166, v[124:127]
	v_mfma_f32_16x16x4_f32 v[128:131], v81, v164, v[76:79]
	v_addc_co_u32_e64 v81, s[0:1], 0, v83, s[0:1]
	s_nop 5
	global_load_dwordx4 v[76:79], v[134:135], off
	s_nop 0
	global_load_dwordx4 v[80:83], v[80:81], off
	ds_read2_b32 v[134:135], v136 offset0:72 offset1:76
	v_add_f32_e32 v124, v167, v124
	v_min_f32_e32 v137, 0, v124
	v_mul_f32_e64 v124, |v124|, s53
	v_exp_f32_e32 v124, v124
	v_add_f32_e32 v126, v167, v126
	v_mul_f32_e64 v133, |v126|, s53
	v_exp_f32_e32 v133, v133
	v_add_f32_e32 v124, 1.0, v124
	v_log_f32_e32 v124, v124
	s_waitcnt lgkmcnt(0)
	v_mfma_f32_16x16x4_f32 v[128:131], v134, v165, v[128:131]
	v_add_f32_e32 v133, 1.0, v133
	v_min_f32_e32 v139, 0, v126
	v_fmac_f32_e32 v137, 0xbf317218, v124
	v_log_f32_e32 v124, v133
	v_add_f32_e32 v134, v167, v127
	v_add_f32_e32 v125, v167, v125
	v_mul_f32_e64 v132, |v125|, s53
	v_fmac_f32_e32 v139, 0xbf317218, v124
	v_mul_f32_e64 v124, |v134|, s53
	v_min_f32_e32 v138, 0, v125
	v_exp_f32_e32 v140, v124
	v_mfma_f32_16x16x4_f32 v[124:127], v135, v166, v[128:131]
	v_exp_f32_e32 v132, v132
	v_add_f32_e32 v129, 1.0, v140
	v_log_f32_e32 v129, v129
	v_add_f32_e32 v132, 1.0, v132
	v_log_f32_e32 v132, v132
	v_min_f32_e32 v140, 0, v134
	s_nop 3
	v_add_f32_e32 v124, v167, v124
	v_mul_f32_e64 v128, |v124|, s53
	v_fmac_f32_e32 v138, 0xbf317218, v132
	v_exp_f32_e32 v128, v128
	ds_read2_b32 v[132:133], v136 offset0:128 offset1:132
	v_min_f32_e32 v141, 0, v124
	v_fmac_f32_e32 v140, 0xbf317218, v129
	v_add_f32_e32 v128, 1.0, v128
	v_log_f32_e32 v128, v128
	ds_read2_b32 v[134:135], v136 offset0:136 offset1:140
	v_add_f32_e32 v124, v167, v125
	v_mul_f32_e64 v125, |v124|, s53
	v_fmac_f32_e32 v141, 0xbf317218, v128
	s_waitcnt lgkmcnt(1)
	v_mfma_f32_16x16x4_f32 v[128:131], v132, v155, 0
	v_add_f32_e32 v132, v167, v126
	v_exp_f32_e32 v125, v125
	v_mul_f32_e64 v126, |v132|, s53
	v_exp_f32_e32 v126, v126
	v_min_f32_e32 v142, 0, v124
	v_add_f32_e32 v124, 1.0, v125
	v_add_f32_e32 v144, v167, v127
	v_mfma_f32_16x16x4_f32 v[128:131], v133, v164, v[128:131]
	v_log_f32_e32 v133, v124
	v_add_f32_e32 v124, 1.0, v126
	v_log_f32_e32 v143, v124
	v_mul_f32_e64 v145, |v144|, s53
	v_fmac_f32_e32 v142, 0xbf317218, v133
	s_waitcnt lgkmcnt(0)
	v_mfma_f32_16x16x4_f32 v[124:127], v134, v165, v[128:131]
	s_nop 2
	v_exp_f32_e32 v128, v145
	v_min_f32_e32 v145, 0, v132
	ds_read2_b32 v[132:133], v136 offset0:192 offset1:196
	v_fmac_f32_e32 v145, 0xbf317218, v143
	v_add_f32_e32 v128, 1.0, v128
	v_log_f32_e32 v128, v128
	v_min_f32_e32 v143, 0, v144
	v_mfma_f32_16x16x4_f32 v[124:127], v135, v166, v[124:127]
	v_fmac_f32_e32 v143, 0xbf317218, v128
	s_nop 8
	v_add_f32_e32 v124, v167, v124
	v_mul_f32_e64 v128, |v124|, s53
	v_exp_f32_e32 v134, v128
	s_waitcnt lgkmcnt(0)
	v_mfma_f32_16x16x4_f32 v[128:131], v132, v155, 0
	v_add_f32_e32 v125, v167, v125
	v_mul_f32_e64 v135, |v125|, s53
	v_exp_f32_e32 v132, v135
	v_min_f32_e32 v144, 0, v124
	v_add_f32_e32 v124, 1.0, v134
	ds_read2_b32 v[134:135], v136 offset0:200 offset1:204
	v_add_f32_e32 v132, 1.0, v132
	v_mfma_f32_16x16x4_f32 v[128:131], v133, v164, v[128:131]
	v_log_f32_e32 v132, v132
	v_log_f32_e32 v124, v124
	v_min_f32_e32 v133, 0, v125
	v_add_f32_e32 v146, v167, v127
	v_fmac_f32_e32 v133, 0xbf317218, v132
	v_add_f32_e32 v132, v167, v126
	v_fmac_f32_e32 v144, 0xbf317218, v124
	v_mul_f32_e64 v124, |v132|, s53
	v_exp_f32_e32 v136, v124
	s_waitcnt lgkmcnt(0)
	v_mfma_f32_16x16x4_f32 v[124:127], v134, v165, v[128:131]
	v_mul_f32_e64 v128, |v146|, s53
	v_exp_f32_e32 v128, v128
	v_add_f32_e32 v130, 1.0, v136
	v_log_f32_e32 v130, v130
	v_min_f32_e32 v129, 0, v132
	v_add_f32_e32 v128, 1.0, v128
	v_log_f32_e32 v128, v128
	v_mfma_f32_16x16x4_f32 v[124:127], v135, v166, v[124:127]
	v_fmac_f32_e32 v129, 0xbf317218, v130
	v_min_f32_e32 v130, 0, v146
	v_fmac_f32_e32 v130, 0xbf317218, v128
	s_nop 6
	v_add_f32_e32 v124, v167, v124
	v_mul_f32_e64 v131, |v124|, s53
	v_exp_f32_e32 v131, v131
	v_add_f32_e32 v125, v167, v125
	v_min_f32_e32 v124, 0, v124
	v_add_f32_e32 v126, v167, v126
	v_add_f32_e32 v128, 1.0, v131
	v_mul_f32_e64 v131, |v125|, s53
	v_log_f32_e32 v128, v128
	v_exp_f32_e32 v131, v131
	v_add_f32_e32 v127, v167, v127
	v_mul_f32_e64 v132, |v127|, s53
	v_fmac_f32_e32 v124, 0xbf317218, v128
	v_add_f32_e32 v128, 1.0, v131
	v_mul_f32_e64 v131, |v126|, s53
	v_log_f32_e32 v128, v128
	v_exp_f32_e32 v131, v131
	v_exp_f32_e32 v132, v132
	v_min_f32_e32 v125, 0, v125
	v_fmac_f32_e32 v125, 0xbf317218, v128
	v_add_f32_e32 v128, 1.0, v131
	v_add_f32_e32 v131, 1.0, v132
	v_log_f32_e32 v131, v131
	v_log_f32_e32 v128, v128
	v_min_f32_e32 v127, 0, v127
	v_min_f32_e32 v126, 0, v126
	v_fmac_f32_e32 v127, 0xbf317218, v131
	v_fmac_f32_e32 v126, 0xbf317218, v128
	v_fma_f32 v127, v127, s54, 0
	v_fmamk_f32 v126, v126, 0x3d800000, v127
	v_fmamk_f32 v125, v125, 0x3d800000, v126
	v_fmamk_f32 v124, v124, 0x3d800000, v125
	v_fmamk_f32 v128, v130, 0x3d800000, v124
	v_fmamk_f32 v129, v129, 0x3d800000, v128
	v_fmamk_f32 v130, v133, 0x3d800000, v129
	v_fmamk_f32 v131, v144, 0x3d800000, v130
	v_fmamk_f32 v132, v143, 0x3d800000, v131
	v_fmamk_f32 v133, v145, 0x3d800000, v132
	v_fmamk_f32 v134, v142, 0x3d800000, v133
	v_fmamk_f32 v135, v141, 0x3d800000, v134
	v_fmamk_f32 v136, v140, 0x3d800000, v135
	v_fmamk_f32 v139, v139, 0x3d800000, v136
	v_fmamk_f32 v138, v138, 0x3d800000, v139
	v_fmamk_f32 v137, v137, 0x3d800000, v138
	v_mov_b32_e32 v252, v137
	v_mov_b32_e32 v253, v137
	s_nop 1
	v_permlane16_swap_b32_e32 v252, v253
	v_mov_b32_e32 v254, v252
	v_mov_b32_e32 v255, v253
	s_nop 1
	v_permlane32_swap_b32_e32 v252, v254
	v_permlane32_swap_b32_e32 v253, v255
	v_mov_b32_e32 v140, v255
	v_mov_b32_e32 v141, v254
	v_mov_b32_e32 v142, v253
	s_waitcnt lgkmcnt(2)
	v_cndmask_b32_e64 v140, v140, 0, s[2:3]
	s_waitcnt lgkmcnt(1)
	v_cndmask_b32_e64 v141, 0, v141, s[4:5]
	v_add_f32_e32 v140, v141, v140
	s_waitcnt lgkmcnt(0)
	v_cndmask_b32_e64 v141, 0, v142, s[6:7]
	v_add_f32_e32 v140, v141, v140
	v_add_f32_e32 v137, v140, v137
	v_add_f32_e32 v138, v140, v138
	v_add_f32_e32 v124, v140, v124
	v_add_f32_e32 v125, v140, v125
	ds_write2st64_b32 v184, v137, v138 offset0:24 offset1:26
	v_add_f32_e32 v137, v140, v139
	v_add_f32_e32 v136, v140, v136
	v_add_f32_e32 v135, v140, v135
	v_add_f32_e32 v134, v140, v134
	v_add_f32_e32 v133, v140, v133
	v_add_f32_e32 v132, v140, v132
	v_add_f32_e32 v131, v140, v131
	v_add_f32_e32 v130, v140, v130
	v_add_f32_e32 v129, v140, v129
	v_add_f32_e32 v128, v140, v128
	ds_write2st64_b32 v184, v124, v125 offset0:48 offset1:50
	v_add_f32_e32 v124, v140, v126
	v_add_f32_e32 v125, v140, v127
	ds_write2st64_b32 v184, v137, v136 offset0:28 offset1:30
	ds_write2st64_b32 v184, v135, v134 offset0:32 offset1:34
	ds_write2st64_b32 v184, v133, v132 offset0:36 offset1:38
	ds_write2st64_b32 v184, v131, v130 offset0:40 offset1:42
	ds_write2st64_b32 v184, v129, v128 offset0:44 offset1:46
	ds_write2st64_b32 v184, v124, v125 offset0:52 offset1:54
	s_waitcnt lgkmcnt(0)
	s_barrier
	s_and_saveexec_b64 s[0:1], s[8:9]
	s_cbranch_execz .LBB0_2185
	ds_read_b32 v124, v175 offset:6144
	v_lshl_add_u32 v125, s57, 9, v175
	s_waitcnt lgkmcnt(0)
	ds_write_b32 v125, v124 offset:4096

.LBB0_2267:
	s_add_u32 s62, s92, s74
	s_addc_u32 s63, s94, s75
	s_add_u32 s49, s53, s74
	s_addc_u32 s61, s55, s75
	v_lshl_add_u64 v[70:71], s[62:63], 0, v[112:113]
	s_add_u32 s62, s49, s0
	v_add_co_u32_e32 v74, vcc, s72, v70
	s_addc_u32 s63, s61, 0
	s_nop 0
	v_addc_co_u32_e32 v75, vcc, 0, v71, vcc
	v_lshl_add_u64 v[86:87], s[62:63], 0, v[114:115]
	v_add_co_u32_e32 v78, vcc, s81, v86
	s_and_b32 s49, s95, 1
	s_add_i32 s89, s1, 0xf0
	v_addc_co_u32_e32 v79, vcc, 0, v87, vcc
	s_cmp_eq_u32 s49, 0
	v_add_co_u32_e32 v82, vcc, s72, v86
	s_cselect_b64 s[76:77], -1, 0
	s_nop 0
	v_addc_co_u32_e32 v83, vcc, 0, v87, vcc
	s_and_b64 s[62:63], s[76:77], exec
	global_load_dwordx4 v[94:97], v[70:71], off
	global_load_dwordx4 v[98:101], v[70:71], off offset:1024
	s_nop 0
	global_load_dwordx4 v[70:73], v[74:75], off
	global_load_dwordx4 v[90:93], v[74:75], off offset:1024
	s_cselect_b32 s61, 0xf0, s89
	global_load_dwordx4 v[74:77], v[86:87], off
	v_add_co_u32_e32 v86, vcc, s73, v86
	v_add3_u32 v137, s61, v180, v116
	s_nop 0
	v_addc_co_u32_e32 v87, vcc, 0, v87, vcc
	global_load_dwordx4 v[78:81], v[78:79], off
	s_nop 0
	global_load_dwordx4 v[82:85], v[82:83], off
	s_nop 0
	global_load_dwordx4 v[86:89], v[86:87], off
	ds_read2_b32 v[108:109], v137 offset1:4
	ds_read2_b32 v[142:143], v137 offset0:8 offset1:12
	s_waitcnt lgkmcnt(1)
	v_mfma_f32_16x16x4_f32 v[138:141], v108, v102, 0
	ds_read2_b32 v[146:147], v137 offset0:128 offset1:132
	v_mfma_f32_16x16x4_f32 v[138:141], v109, v103, v[138:141]
	s_waitcnt lgkmcnt(1)
	v_mfma_f32_16x16x4_f32 v[138:141], v142, v104, v[138:141]
	v_mfma_f32_16x16x4_f32 v[138:141], v143, v105, v[138:141]
	ds_read2_b32 v[142:143], v137 offset0:64 offset1:68
	s_nop 8
	v_add_f32_e32 v108, v106, v138
	v_min_f32_e32 v107, 0, v108
	v_mul_f32_e64 v108, |v108|, s66
	v_exp_f32_e32 v108, v108
	v_add_f32_e32 v109, v106, v139
	v_add_f32_e32 v135, v106, v140
	v_add_f32_e32 v138, v106, v141
	v_add_f32_e32 v108, 1.0, v108
	v_log_f32_e32 v108, v108
	s_nop 0
	v_fmac_f32_e32 v107, 0xbf317218, v108
	v_min_f32_e32 v108, 0, v109
	v_mul_f32_e64 v109, |v109|, s66
	v_exp_f32_e32 v109, v109
	v_fma_f32 v107, v107, s67, 0
	v_add_f32_e32 v109, 1.0, v109
	v_log_f32_e32 v109, v109
	s_nop 0
	v_fmac_f32_e32 v108, 0xbf317218, v109
	v_min_f32_e32 v109, 0, v135
	v_mul_f32_e64 v135, |v135|, s66
	v_exp_f32_e32 v135, v135
	v_fmamk_f32 v108, v108, 0x3d800000, v107
	v_add_f32_e32 v135, 1.0, v135
	v_log_f32_e32 v135, v135
	s_nop 0
	v_fmac_f32_e32 v109, 0xbf317218, v135
	v_min_f32_e32 v135, 0, v138
	v_mul_f32_e64 v138, |v138|, s66
	v_exp_f32_e32 v138, v138
	v_fmamk_f32 v109, v109, 0x3d800000, v108
	v_add_f32_e32 v138, 1.0, v138
	v_log_f32_e32 v138, v138
	s_nop 0
	v_fmac_f32_e32 v135, 0xbf317218, v138
	s_waitcnt lgkmcnt(0)
	v_mfma_f32_16x16x4_f32 v[138:141], v142, v102, 0
	v_fmamk_f32 v135, v135, 0x3d800000, v109
	v_mfma_f32_16x16x4_f32 v[138:141], v143, v103, v[138:141]
	ds_read2_b32 v[142:143], v137 offset0:72 offset1:76
	s_waitcnt lgkmcnt(0)
	v_mfma_f32_16x16x4_f32 v[138:141], v142, v104, v[138:141]
	v_mfma_f32_16x16x4_f32 v[138:141], v143, v105, v[138:141]
	s_nop 9
	v_add_f32_e32 v142, v106, v138
	v_min_f32_e32 v138, 0, v142
	v_mul_f32_e64 v142, |v142|, s66
	v_exp_f32_e32 v142, v142
	s_nop 0
	v_add_f32_e32 v142, 1.0, v142
	v_log_f32_e32 v142, v142
	s_nop 0
	v_fmac_f32_e32 v138, 0xbf317218, v142
	v_add_f32_e32 v142, v106, v139
	v_min_f32_e32 v139, 0, v142
	v_mul_f32_e64 v142, |v142|, s66
	v_exp_f32_e32 v142, v142
	s_nop 0
	v_add_f32_e32 v142, 1.0, v142
	v_log_f32_e32 v142, v142
	s_nop 0
	v_fmac_f32_e32 v139, 0xbf317218, v142
	v_add_f32_e32 v142, v106, v140
	v_min_f32_e32 v140, 0, v142
	v_mul_f32_e64 v142, |v142|, s66
	v_exp_f32_e32 v142, v142
	s_nop 0
	v_add_f32_e32 v142, 1.0, v142
	v_log_f32_e32 v142, v142
	s_nop 0
	v_fmac_f32_e32 v140, 0xbf317218, v142
	v_add_f32_e32 v142, v106, v141
	v_min_f32_e32 v141, 0, v142
	v_mul_f32_e64 v142, |v142|, s66
	v_exp_f32_e32 v142, v142
	s_nop 0
	v_add_f32_e32 v142, 1.0, v142
	v_log_f32_e32 v142, v142
	s_nop 0
	v_fmac_f32_e32 v141, 0xbf317218, v142
	v_mfma_f32_16x16x4_f32 v[142:145], v146, v102, 0
	v_mfma_f32_16x16x4_f32 v[142:145], v147, v103, v[142:145]
	ds_read2_b32 v[146:147], v137 offset0:136 offset1:140
	s_waitcnt lgkmcnt(0)
	v_mfma_f32_16x16x4_f32 v[142:145], v146, v104, v[142:145]
	v_mfma_f32_16x16x4_f32 v[142:145], v147, v105, v[142:145]
	ds_read2_b32 v[146:147], v137 offset0:192 offset1:196
	s_nop 8
	v_add_f32_e32 v142, v106, v142
	v_min_f32_e32 v148, 0, v142
	v_mul_f32_e64 v142, |v142|, s66
	v_exp_f32_e32 v142, v142
	s_nop 0
	v_add_f32_e32 v142, 1.0, v142
	v_log_f32_e32 v142, v142
	s_nop 0
	v_fmac_f32_e32 v148, 0xbf317218, v142
	v_add_f32_e32 v142, v106, v143
	v_min_f32_e32 v149, 0, v142
	v_mul_f32_e64 v142, |v142|, s66
	v_exp_f32_e32 v142, v142
	s_nop 0
	v_add_f32_e32 v142, 1.0, v142
	v_log_f32_e32 v142, v142
	s_nop 0
	v_fmac_f32_e32 v149, 0xbf317218, v142
	v_add_f32_e32 v142, v106, v144
	v_min_f32_e32 v150, 0, v142
	v_mul_f32_e64 v142, |v142|, s66
	v_exp_f32_e32 v142, v142
	s_nop 0
	v_add_f32_e32 v142, 1.0, v142
	v_log_f32_e32 v142, v142
	s_nop 0
	v_fmac_f32_e32 v150, 0xbf317218, v142
	v_add_f32_e32 v142, v106, v145
	v_min_f32_e32 v151, 0, v142
	v_mul_f32_e64 v142, |v142|, s66
	v_exp_f32_e32 v142, v142
	s_nop 0
	v_add_f32_e32 v142, 1.0, v142
	v_log_f32_e32 v142, v142
	s_nop 0
	v_fmac_f32_e32 v151, 0xbf317218, v142
	s_waitcnt lgkmcnt(0)
	v_mfma_f32_16x16x4_f32 v[142:145], v146, v102, 0
	v_mfma_f32_16x16x4_f32 v[142:145], v147, v103, v[142:145]
	ds_read2_b32 v[146:147], v137 offset0:200 offset1:204
	s_waitcnt lgkmcnt(0)
	v_mfma_f32_16x16x4_f32 v[142:145], v146, v104, v[142:145]
	v_mfma_f32_16x16x4_f32 v[142:145], v147, v105, v[142:145]
	s_nop 9
	v_add_f32_e32 v137, v106, v142
	v_min_f32_e32 v142, 0, v137
	v_mul_f32_e64 v137, |v137|, s66
	v_exp_f32_e32 v137, v137
	s_nop 0
	v_add_f32_e32 v137, 1.0, v137
	v_log_f32_e32 v137, v137
	s_nop 0
	v_fmac_f32_e32 v142, 0xbf317218, v137
	v_add_f32_e32 v137, v106, v143
	v_min_f32_e32 v143, 0, v137
	v_mul_f32_e64 v137, |v137|, s66
	v_exp_f32_e32 v137, v137
	s_nop 0
	v_add_f32_e32 v137, 1.0, v137
	v_log_f32_e32 v137, v137
	s_nop 0
	v_fmac_f32_e32 v143, 0xbf317218, v137
	v_add_f32_e32 v137, v106, v144
	v_min_f32_e32 v144, 0, v137
	v_mul_f32_e64 v137, |v137|, s66
	v_exp_f32_e32 v137, v137
	s_nop 0
	v_add_f32_e32 v137, 1.0, v137
	v_log_f32_e32 v137, v137
	s_nop 0
	v_fmac_f32_e32 v144, 0xbf317218, v137
	v_add_f32_e32 v137, v106, v145
	v_min_f32_e32 v145, 0, v137
	v_mul_f32_e64 v137, |v137|, s66
	v_exp_f32_e32 v137, v137
	s_nop 0
	v_add_f32_e32 v137, 1.0, v137
	v_log_f32_e32 v137, v137
	s_nop 0
	v_fmac_f32_e32 v145, 0xbf317218, v137
	v_fmamk_f32 v137, v138, 0x3d800000, v135
	v_fmamk_f32 v138, v139, 0x3d800000, v137
	v_fmamk_f32 v139, v140, 0x3d800000, v138
	v_fmamk_f32 v140, v141, 0x3d800000, v139
	v_fmamk_f32 v141, v148, 0x3d800000, v140
	v_fmamk_f32 v146, v149, 0x3d800000, v141
	v_fmamk_f32 v147, v150, 0x3d800000, v146
	v_fmamk_f32 v148, v151, 0x3d800000, v147
	v_fmamk_f32 v142, v142, 0x3d800000, v148
	v_fmamk_f32 v143, v143, 0x3d800000, v142
	v_fmamk_f32 v144, v144, 0x3d800000, v143
	v_fmamk_f32 v145, v145, 0x3d800000, v144
	v_mov_b32_e32 v252, v145
	v_mov_b32_e32 v253, v145
	s_nop 1
	v_permlane16_swap_b32_e32 v252, v253
	v_mov_b32_e32 v254, v252
	v_mov_b32_e32 v255, v253
	s_nop 1
	v_permlane32_swap_b32_e32 v252, v254
	v_permlane32_swap_b32_e32 v253, v255
	v_mov_b32_e32 v149, v252
	v_mov_b32_e32 v150, v253
	v_mov_b32_e32 v151, v254
	s_waitcnt lgkmcnt(2)
	v_cndmask_b32_e64 v149, v149, 0, s[4:5]
	s_waitcnt lgkmcnt(1)
	v_cndmask_b32_e64 v150, 0, v150, s[6:7]
	v_add_f32_e32 v149, v149, v150
	s_waitcnt lgkmcnt(0)
	v_cndmask_b32_e64 v150, 0, v151, s[8:9]
	v_add_f32_e32 v149, v149, v150
	v_add_f32_e32 v107, v107, v149
	v_add_f32_e32 v108, v108, v149
	ds_write2st64_b32 v204, v107, v108 offset0:24 offset1:26
	v_add_f32_e32 v107, v109, v149
	v_add_f32_e32 v108, v135, v149
	ds_write2st64_b32 v204, v107, v108 offset0:28 offset1:30
	v_add_f32_e32 v107, v137, v149
	v_add_f32_e32 v108, v138, v149
	ds_write2st64_b32 v204, v107, v108 offset0:32 offset1:34
	v_add_f32_e32 v107, v139, v149
	v_add_f32_e32 v108, v140, v149
	ds_write2st64_b32 v204, v107, v108 offset0:36 offset1:38
	v_add_f32_e32 v107, v141, v149
	v_add_f32_e32 v108, v146, v149
	ds_write2st64_b32 v204, v107, v108 offset0:40 offset1:42
	v_add_f32_e32 v107, v149, v147
	v_add_f32_e32 v108, v149, v148
	ds_write2st64_b32 v204, v107, v108 offset0:44 offset1:46
	v_add_f32_e32 v107, v149, v142
	v_add_f32_e32 v108, v149, v143
	ds_write2st64_b32 v204, v107, v108 offset0:48 offset1:50
	v_add_f32_e32 v107, v149, v144
	v_add_f32_e32 v108, v149, v145
	ds_write2st64_b32 v204, v107, v108 offset0:52 offset1:54
	s_waitcnt lgkmcnt(0)
	s_barrier
	s_and_saveexec_b64 s[62:63], s[10:11]
	s_cbranch_execz .LBB0_2269
	ds_read_b32 v107, v181 offset:38400
	v_lshl_add_u32 v108, s49, 9, v181
	s_waitcnt lgkmcnt(0)
	ds_write_b32 v108, v107 offset:4096

.LBB0_2283:
	s_add_u32 s60, s70, s58
	s_addc_u32 s61, s71, s59
	s_add_u32 s49, s64, s58
	s_addc_u32 s69, s65, s59
	s_add_u32 s53, s49, s0
	v_lshl_add_u64 v[70:71], s[60:61], 0, v[112:113]
	s_addc_u32 s61, s69, 0
	s_add_u32 s60, s53, 0xafc0800
	v_add_co_u32_e32 v74, vcc, s72, v70
	s_addc_u32 s61, s61, 0
	s_nop 0
	v_addc_co_u32_e32 v75, vcc, 0, v71, vcc
	v_lshl_add_u64 v[86:87], s[60:61], 0, v[114:115]
	v_add_co_u32_e32 v78, vcc, s81, v86
	s_and_b32 s68, s74, 1
	s_nop 0
	v_addc_co_u32_e32 v79, vcc, 0, v87, vcc
	s_cmp_eq_u32 s68, 0
	v_add_co_u32_e32 v82, vcc, s72, v86
	s_cselect_b64 s[60:61], -1, 0
	s_nop 0
	v_addc_co_u32_e32 v83, vcc, 0, v87, vcc
	s_and_b64 s[62:63], s[60:61], exec
	global_load_dwordx4 v[94:97], v[70:71], off
	global_load_dwordx4 v[98:101], v[70:71], off offset:1024
	s_nop 0
	global_load_dwordx4 v[70:73], v[74:75], off
	global_load_dwordx4 v[90:93], v[74:75], off offset:1024
	s_cselect_b32 s53, 0xf0, s89
	global_load_dwordx4 v[74:77], v[86:87], off
	v_add_co_u32_e32 v86, vcc, s73, v86
	v_add3_u32 v105, s53, v180, v116
	s_nop 0
	v_addc_co_u32_e32 v87, vcc, 0, v87, vcc
	global_load_dwordx4 v[78:81], v[78:79], off
	s_nop 0
	global_load_dwordx4 v[82:85], v[82:83], off
	s_nop 0
	global_load_dwordx4 v[86:89], v[86:87], off
	ds_read2_b32 v[102:103], v105 offset1:4
	ds_read2_b32 v[140:141], v105 offset0:8 offset1:12
	s_waitcnt vmcnt(12) lgkmcnt(1)
	v_mfma_f32_16x16x4_f32 v[106:109], v102, v223, 0
	ds_read2_b32 v[144:145], v105 offset0:128 offset1:132
	s_waitcnt vmcnt(11)
	v_mfma_f32_16x16x4_f32 v[106:109], v103, v224, v[106:109]
	s_waitcnt vmcnt(10) lgkmcnt(1)
	v_mfma_f32_16x16x4_f32 v[106:109], v140, v225, v[106:109]
	s_waitcnt vmcnt(9)
	v_mfma_f32_16x16x4_f32 v[106:109], v141, v226, v[106:109]
	ds_read2_b32 v[140:141], v105 offset0:64 offset1:68
	s_waitcnt vmcnt(8)
	s_nop 7
	v_add_f32_e32 v102, v227, v106
	v_min_f32_e32 v0, 0, v102
	v_mul_f32_e64 v102, |v102|, s66
	v_exp_f32_e32 v102, v102
	v_add_f32_e32 v103, v227, v107
	v_add_f32_e32 v104, v227, v108
	v_add_f32_e32 v106, v227, v109
	v_add_f32_e32 v102, 1.0, v102
	v_log_f32_e32 v102, v102
	s_nop 0
	v_fmac_f32_e32 v0, 0xbf317218, v102
	v_min_f32_e32 v102, 0, v103
	v_mul_f32_e64 v103, |v103|, s66
	v_exp_f32_e32 v103, v103
	s_nop 0
	v_add_f32_e32 v103, 1.0, v103
	v_log_f32_e32 v103, v103
	s_nop 0
	v_fmac_f32_e32 v102, 0xbf317218, v103
	v_min_f32_e32 v103, 0, v104
	v_mul_f32_e64 v104, |v104|, s66
	v_exp_f32_e32 v104, v104
	s_nop 0
	v_add_f32_e32 v104, 1.0, v104
	v_log_f32_e32 v104, v104
	s_nop 0
	v_fmac_f32_e32 v103, 0xbf317218, v104
	v_min_f32_e32 v104, 0, v106
	v_mul_f32_e64 v106, |v106|, s66
	v_exp_f32_e32 v106, v106
	s_nop 0
	v_add_f32_e32 v106, 1.0, v106
	v_log_f32_e32 v106, v106
	s_nop 0
	v_fmac_f32_e32 v104, 0xbf317218, v106
	s_waitcnt lgkmcnt(0)
	v_mfma_f32_16x16x4_f32 v[106:109], v140, v223, 0
	v_mfma_f32_16x16x4_f32 v[106:109], v141, v224, v[106:109]
	ds_read2_b32 v[140:141], v105 offset0:72 offset1:76
	s_waitcnt lgkmcnt(0)
	v_mfma_f32_16x16x4_f32 v[106:109], v140, v225, v[106:109]
	v_mfma_f32_16x16x4_f32 v[106:109], v141, v226, v[106:109]
	v_mfma_f32_16x16x4_f32 v[140:143], v144, v223, 0
	s_nop 8
	v_add_f32_e32 v135, v227, v106
	v_min_f32_e32 v106, 0, v135
	v_mul_f32_e64 v135, |v135|, s66
	v_exp_f32_e32 v135, v135
	s_nop 0
	v_add_f32_e32 v135, 1.0, v135
	v_log_f32_e32 v135, v135
	v_mfma_f32_16x16x4_f32 v[140:143], v145, v224, v[140:143]
	ds_read2_b32 v[144:145], v105 offset0:136 offset1:140
	v_fmac_f32_e32 v106, 0xbf317218, v135
	v_add_f32_e32 v135, v227, v107
	v_min_f32_e32 v107, 0, v135
	v_mul_f32_e64 v135, |v135|, s66
	v_exp_f32_e32 v135, v135
	s_waitcnt lgkmcnt(0)
	v_mfma_f32_16x16x4_f32 v[140:143], v144, v225, v[140:143]
	v_add_f32_e32 v135, 1.0, v135
	v_log_f32_e32 v135, v135
	s_nop 0
	v_fmac_f32_e32 v107, 0xbf317218, v135
	v_add_f32_e32 v135, v227, v108
	v_min_f32_e32 v108, 0, v135
	v_mul_f32_e64 v135, |v135|, s66
	v_exp_f32_e32 v135, v135
	v_mfma_f32_16x16x4_f32 v[140:143], v145, v226, v[140:143]
	ds_read2_b32 v[144:145], v105 offset0:192 offset1:196
	v_add_f32_e32 v135, 1.0, v135
	v_log_f32_e32 v135, v135
	s_nop 0
	v_fmac_f32_e32 v108, 0xbf317218, v135
	v_add_f32_e32 v135, v227, v109
	v_min_f32_e32 v109, 0, v135
	v_mul_f32_e64 v135, |v135|, s66
	v_exp_f32_e32 v135, v135
	s_nop 0
	v_add_f32_e32 v135, 1.0, v135
	v_log_f32_e32 v135, v135
	s_nop 0
	v_fmac_f32_e32 v109, 0xbf317218, v135
	v_add_f32_e32 v135, v227, v140
	v_min_f32_e32 v137, 0, v135
	v_mul_f32_e64 v135, |v135|, s66
	v_exp_f32_e32 v135, v135
	s_nop 0
	v_add_f32_e32 v135, 1.0, v135
	v_log_f32_e32 v135, v135
	s_nop 0
	v_fmac_f32_e32 v137, 0xbf317218, v135
	v_add_f32_e32 v135, v227, v141
	v_min_f32_e32 v146, 0, v135
	v_mul_f32_e64 v135, |v135|, s66
	v_exp_f32_e32 v135, v135
	s_nop 0
	v_add_f32_e32 v135, 1.0, v135
	v_log_f32_e32 v135, v135
	s_nop 0
	v_fmac_f32_e32 v146, 0xbf317218, v135
	v_add_f32_e32 v135, v227, v142
	v_min_f32_e32 v147, 0, v135
	v_mul_f32_e64 v135, |v135|, s66
	v_exp_f32_e32 v135, v135
	s_nop 0
	v_add_f32_e32 v135, 1.0, v135
	v_log_f32_e32 v135, v135
	s_nop 0
	v_fmac_f32_e32 v147, 0xbf317218, v135
	v_add_f32_e32 v135, v227, v143
	s_waitcnt lgkmcnt(0)
	v_mfma_f32_16x16x4_f32 v[140:143], v144, v223, 0
	v_min_f32_e32 v148, 0, v135
	v_mul_f32_e64 v135, |v135|, s66
	v_exp_f32_e32 v135, v135
	s_nop 0
	v_add_f32_e32 v135, 1.0, v135
	v_mfma_f32_16x16x4_f32 v[140:143], v145, v224, v[140:143]
	ds_read2_b32 v[144:145], v105 offset0:200 offset1:204
	v_log_f32_e32 v135, v135
	s_nop 0
	v_fmac_f32_e32 v148, 0xbf317218, v135
	s_waitcnt lgkmcnt(0)
	v_mfma_f32_16x16x4_f32 v[140:143], v144, v225, v[140:143]
	v_mfma_f32_16x16x4_f32 v[140:143], v145, v226, v[140:143]
	s_nop 9
	v_add_f32_e32 v105, v227, v140
	v_min_f32_e32 v135, 0, v105
	v_mul_f32_e64 v105, |v105|, s66
	v_exp_f32_e32 v105, v105
	s_nop 0
	v_add_f32_e32 v105, 1.0, v105
	v_log_f32_e32 v105, v105
	s_nop 0
	v_fmac_f32_e32 v135, 0xbf317218, v105
	v_add_f32_e32 v105, v227, v141
	v_min_f32_e32 v140, 0, v105
	v_mul_f32_e64 v105, |v105|, s66
	v_exp_f32_e32 v105, v105
	s_nop 0
	v_add_f32_e32 v105, 1.0, v105
	v_log_f32_e32 v105, v105
	s_nop 0
	v_fmac_f32_e32 v140, 0xbf317218, v105
	v_add_f32_e32 v105, v227, v142
	v_min_f32_e32 v141, 0, v105
	v_mul_f32_e64 v105, |v105|, s66
	v_exp_f32_e32 v105, v105
	s_nop 0
	v_add_f32_e32 v105, 1.0, v105
	v_log_f32_e32 v105, v105
	s_nop 0
	v_fmac_f32_e32 v141, 0xbf317218, v105
	v_add_f32_e32 v105, v227, v143
	v_min_f32_e32 v142, 0, v105
	v_mul_f32_e64 v105, |v105|, s66
	v_exp_f32_e32 v105, v105
	s_nop 0
	v_add_f32_e32 v105, 1.0, v105
	v_log_f32_e32 v105, v105
	s_nop 0
	v_fmac_f32_e32 v142, 0xbf317218, v105
	v_fma_f32 v105, v142, s67, 0
	v_fmamk_f32 v141, v141, 0x3d800000, v105
	v_fmamk_f32 v140, v140, 0x3d800000, v141
	v_fmamk_f32 v135, v135, 0x3d800000, v140
	v_fmamk_f32 v142, v148, 0x3d800000, v135
	v_fmamk_f32 v143, v147, 0x3d800000, v142
	v_fmamk_f32 v144, v146, 0x3d800000, v143
	v_fmamk_f32 v137, v137, 0x3d800000, v144
	v_fmamk_f32 v109, v109, 0x3d800000, v137
	v_fmamk_f32 v108, v108, 0x3d800000, v109
	v_fmamk_f32 v107, v107, 0x3d800000, v108
	v_fmamk_f32 v106, v106, 0x3d800000, v107
	v_fmamk_f32 v104, v104, 0x3d800000, v106
	v_fmamk_f32 v103, v103, 0x3d800000, v104
	v_fmamk_f32 v102, v102, 0x3d800000, v103
	v_fmamk_f32 v0, v0, 0x3d800000, v102
	v_mov_b32_e32 v252, v0
	v_mov_b32_e32 v253, v0
	s_nop 1
	v_permlane16_swap_b32_e32 v252, v253
	v_mov_b32_e32 v254, v252
	v_mov_b32_e32 v255, v253
	s_nop 1
	v_permlane32_swap_b32_e32 v252, v254
	v_permlane32_swap_b32_e32 v253, v255
	v_mov_b32_e32 v146, v254
	v_mov_b32_e32 v147, v255
	v_mov_b32_e32 v145, v253
	s_waitcnt lgkmcnt(2)
	v_cndmask_b32_e64 v146, 0, v146, s[28:29]
	s_waitcnt lgkmcnt(1)
	v_cndmask_b32_e64 v147, v147, 0, s[8:9]
	v_add_f32_e32 v146, v146, v147
	s_waitcnt lgkmcnt(0)
	v_cndmask_b32_e64 v145, 0, v145, s[4:5]
	v_add_f32_e32 v145, v145, v146
	v_add_f32_e32 v0, v145, v0
	v_add_f32_e32 v102, v145, v102
	ds_write2st64_b32 v204, v0, v102 offset0:24 offset1:26
	v_add_f32_e32 v0, v145, v103
	v_add_f32_e32 v102, v145, v104
	ds_write2st64_b32 v204, v0, v102 offset0:28 offset1:30
	v_add_f32_e32 v0, v145, v106
	v_add_f32_e32 v102, v145, v107
	ds_write2st64_b32 v204, v0, v102 offset0:32 offset1:34
	v_add_f32_e32 v0, v145, v108
	v_add_f32_e32 v102, v145, v109
	ds_write2st64_b32 v204, v0, v102 offset0:36 offset1:38
	v_add_f32_e32 v0, v145, v137
	v_add_f32_e32 v102, v145, v144
	ds_write2st64_b32 v204, v0, v102 offset0:40 offset1:42
	v_add_f32_e32 v0, v145, v143
	v_add_f32_e32 v102, v145, v142
	ds_write2st64_b32 v204, v0, v102 offset0:44 offset1:46
	v_add_f32_e32 v0, v145, v135
	v_add_f32_e32 v102, v145, v140
	ds_write2st64_b32 v204, v0, v102 offset0:48 offset1:50
	v_add_f32_e32 v0, v145, v141
	v_add_f32_e32 v102, v145, v105
	ds_write2st64_b32 v204, v0, v102 offset0:52 offset1:54
	s_waitcnt lgkmcnt(0)
	s_barrier
	s_and_saveexec_b64 s[62:63], s[10:11]
	s_cbranch_execz .LBB0_2285
	ds_read_b32 v0, v181 offset:6144
	v_lshl_add_u32 v102, s68, 9, v181
	s_waitcnt lgkmcnt(0)
	ds_write_b32 v102, v0 offset:4096
